# acc zero-init with 64-bit moves; attention score scaling with plain multiplies instead of move+packed multiply
# baseline (speedup 1.0000x reference)
.LBB0_137:
	s_ashr_i32 s49, s48, 31
	s_lshl_b64 s[22:23], s[48:49], 20
	s_add_u32 s52, s26, s22
	s_addc_u32 s53, s27, s23
	s_and_b64 s[0:1], s[0:1], exec
	s_cselect_b32 s22, s53, s7
	s_cselect_b32 s23, s52, s6
	s_add_u32 s0, s12, 0x80080
	s_addc_u32 s1, s13, 0
	s_add_u32 s38, s6, 0x100
	v_mov_b64_e32 v[2:3], 0
	s_addc_u32 s39, s7, 0
	s_mov_b32 s49, -2
	v_mov_b64_e32 v[4:5], 0
	v_mov_b64_e32 v[6:7], 0
	v_mov_b64_e32 v[8:9], 0
	v_mov_b64_e32 v[10:11], 0
	v_mov_b64_e32 v[12:13], 0
	v_mov_b64_e32 v[14:15], 0
	v_mov_b64_e32 v[16:17], 0
	v_mov_b64_e32 v[18:19], 0
	v_mov_b64_e32 v[20:21], 0
	v_mov_b64_e32 v[22:23], 0
	v_mov_b64_e32 v[24:25], 0
	v_mov_b64_e32 v[26:27], 0
	v_mov_b64_e32 v[28:29], 0
	v_mov_b64_e32 v[30:31], 0
	v_mov_b64_e32 v[32:33], 0
	v_mov_b64_e32 v[34:35], 0
	v_mov_b64_e32 v[36:37], 0
	v_mov_b64_e32 v[38:39], 0
	v_mov_b64_e32 v[40:41], 0
	v_mov_b64_e32 v[42:43], 0
	v_mov_b64_e32 v[44:45], 0
	v_mov_b64_e32 v[46:47], 0
	v_mov_b64_e32 v[48:49], 0
	v_mov_b64_e32 v[50:51], 0
	v_mov_b64_e32 v[52:53], 0
	v_mov_b64_e32 v[54:55], 0
	v_mov_b64_e32 v[56:57], 0
	v_mov_b64_e32 v[58:59], 0
	v_mov_b64_e32 v[60:61], 0
	v_mov_b64_e32 v[62:63], 0
	v_mov_b64_e32 v[64:65], 0
	v_mov_b64_e32 v[66:67], 0
	v_mov_b64_e32 v[68:69], 0
	v_mov_b64_e32 v[70:71], 0
	v_mov_b64_e32 v[72:73], 0
	v_mov_b64_e32 v[74:75], 0
	v_mov_b64_e32 v[76:77], 0
	v_mov_b64_e32 v[78:79], 0
	v_mov_b64_e32 v[80:81], 0
	v_mov_b64_e32 v[82:83], 0
	v_mov_b64_e32 v[84:85], 0
	v_mov_b64_e32 v[86:87], 0
	v_mov_b64_e32 v[88:89], 0
	v_mov_b64_e32 v[90:91], 0
	v_mov_b64_e32 v[92:93], 0
	v_mov_b64_e32 v[94:95], 0
	v_mov_b64_e32 v[96:97], 0
	v_mov_b64_e32 v[98:99], 0
	v_mov_b64_e32 v[100:101], 0
	v_mov_b64_e32 v[102:103], 0
	v_mov_b64_e32 v[104:105], 0
	v_mov_b64_e32 v[106:107], 0
	v_mov_b64_e32 v[108:109], 0
	v_mov_b64_e32 v[110:111], 0
	v_mov_b64_e32 v[112:113], 0
	v_mov_b64_e32 v[114:115], 0
	v_mov_b64_e32 v[116:117], 0
	v_mov_b64_e32 v[118:119], 0
	v_mov_b64_e32 v[120:121], 0
	v_mov_b64_e32 v[122:123], 0
	v_mov_b64_e32 v[124:125], 0
	v_mov_b64_e32 v[126:127], 0
	v_mov_b64_e32 v[128:129], 0
	v_add_u32_e32 v224, 0x10000, v149
	v_add_u32_e32 v225, 0x14000, v149
	v_add_u32_e32 v226, 0x18000, v149
	v_add_u32_e32 v227, 0x1c000, v149

.LBB0_372:
	s_mul_i32 s23, s79, 0x4400
	v_add_u32_e32 v88, s23, v187
	ds_read_b128 v[80:83], v88
	ds_read_b128 v[152:155], v88 offset:32
	ds_read_b128 v[168:171], v88 offset:64
	ds_read_b128 v[172:175], v88 offset:96
	ds_read_b128 v[84:87], v88 offset:8704
	ds_read_b128 v[200:203], v88 offset:8736
	ds_read_b128 v[204:207], v88 offset:8768
	ds_read_b128 v[216:219], v88 offset:8800
	s_waitcnt lgkmcnt(0)
	s_add_i32 s82, s78, s77
	s_waitcnt lgkmcnt(7)
	v_mfma_f32_32x32x16_bf16 v[96:111], v[80:83], v[112:115], 0
	s_cmp_ge_u32 s22, s66
	s_cselect_b64 s[42:43], -1, 0
	s_cmp_lt_u32 s22, 2
	s_cselect_b64 s[22:23], -1, 0
	s_or_b64 s[22:23], s[22:23], s[42:43]
	s_andn2_b64 vcc, exec, s[22:23]
	s_waitcnt lgkmcnt(3)
	v_mfma_f32_32x32x16_bf16 v[80:95], v[84:87], v[112:115], 0
	v_mfma_f32_32x32x16_bf16 v[96:111], v[152:155], v[116:119], v[96:111]
	s_waitcnt lgkmcnt(2)
	v_mfma_f32_32x32x16_bf16 v[80:95], v[200:203], v[116:119], v[80:95]
	v_mfma_f32_32x32x16_bf16 v[96:111], v[168:171], v[120:123], v[96:111]
	s_waitcnt lgkmcnt(1)
	v_mfma_f32_32x32x16_bf16 v[80:95], v[204:207], v[120:123], v[80:95]
	v_mfma_f32_32x32x16_bf16 v[96:111], v[172:175], v[124:127], v[96:111]
	s_waitcnt lgkmcnt(0)
	v_mfma_f32_32x32x16_bf16 v[80:95], v[216:219], v[124:127], v[80:95]
	s_nop 9
	v_mul_f32_e64 v168, v102, s24
	v_mul_f32_e64 v169, v103, s24
	v_mul_f32_e64 v102, v104, s24
	v_mul_f32_e64 v103, v105, s24
	v_mul_f32_e64 v172, v96, s24
	v_mul_f32_e64 v173, v97, s24
	v_pk_mul_f32 v[174:175], v[98:99], s[24:25] op_sel_hi:[1,0]
	v_pk_mul_f32 v[170:171], v[100:101], s[24:25] op_sel_hi:[1,0]
	v_pk_mul_f32 v[100:101], v[106:107], s[24:25] op_sel_hi:[1,0]
	v_pk_mul_f32 v[98:99], v[108:109], s[24:25] op_sel_hi:[1,0]
	v_mul_f32_e32 v105, 0x3e38aa3b, v80
	v_pk_mul_f32 v[96:97], v[110:111], s[24:25] op_sel_hi:[1,0]
	v_mul_f32_e32 v80, 0x3e38aa3b, v81
	v_mul_f32_e32 v81, 0x3e38aa3b, v82
	v_mul_f32_e32 v82, 0x3e38aa3b, v83
	v_mul_f32_e32 v83, 0x3e38aa3b, v84
	v_mul_f32_e32 v84, 0x3e38aa3b, v85
	v_mul_f32_e32 v85, 0x3e38aa3b, v86
	v_mul_f32_e32 v86, 0x3e38aa3b, v87
	v_mul_f32_e32 v87, 0x3e38aa3b, v88
	v_mul_f32_e32 v88, 0x3e38aa3b, v89
	v_mul_f32_e32 v89, 0x3e38aa3b, v90
	v_mul_f32_e32 v90, 0x3e38aa3b, v91
	v_mul_f32_e32 v91, 0x3e38aa3b, v92
	v_mul_f32_e32 v92, 0x3e38aa3b, v93
	v_mul_f32_e32 v93, 0x3e38aa3b, v94
	v_mul_f32_e32 v94, 0x3e38aa3b, v95
	s_cbranch_vccnz .LBB0_374
	s_cmpk_gt_u32 s82, 0x6f
	v_add_u32_e32 v95, s77, v188
	s_cselect_b64 s[22:23], -1, 0
	v_cmp_eq_u32_e32 vcc, s77, v198
	s_or_b64 s[42:43], s[22:23], vcc
	v_cmp_le_u32_e32 vcc, v95, v158
	v_add_u32_e32 v104, s77, v197
	s_and_b64 vcc, vcc, s[42:43]
	v_cmp_eq_u32_e64 s[42:43], 0, v104
	v_cndmask_b32_e32 v172, v214, v172, vcc
	v_cmp_lt_u32_e32 vcc, v95, v158
	s_or_b64 s[42:43], s[22:23], s[42:43]
	v_add_u32_e32 v104, s77, v196
	s_and_b64 vcc, vcc, s[42:43]
	v_add_u32_e32 v106, 2, v95
	v_cmp_eq_u32_e64 s[42:43], 0, v104
	v_cndmask_b32_e32 v173, v214, v173, vcc
	v_cmp_le_u32_e32 vcc, v106, v158
	s_or_b64 s[42:43], s[22:23], s[42:43]
	v_add_u32_e32 v104, s77, v195
	s_and_b64 vcc, vcc, s[42:43]
	v_add_u32_e32 v106, 3, v95
	v_cmp_eq_u32_e64 s[42:43], 0, v104
	v_cndmask_b32_e32 v174, v214, v174, vcc
	v_cmp_le_u32_e32 vcc, v106, v158
	s_or_b64 s[42:43], s[22:23], s[42:43]
	v_add_u32_e32 v104, s77, v194
	s_and_b64 vcc, vcc, s[42:43]
	v_add_u32_e32 v106, 8, v95
	v_cmp_eq_u32_e64 s[42:43], 0, v104
	v_cndmask_b32_e32 v175, v214, v175, vcc
	v_cmp_le_u32_e32 vcc, v106, v158
	s_or_b64 s[42:43], s[22:23], s[42:43]
	v_add_u32_e32 v104, s77, v193
	s_and_b64 vcc, vcc, s[42:43]
	v_add_u32_e32 v106, 9, v95
	v_cmp_eq_u32_e64 s[42:43], 0, v104
	v_cndmask_b32_e32 v170, v214, v170, vcc
	v_cmp_le_u32_e32 vcc, v106, v158
	s_or_b64 s[42:43], s[22:23], s[42:43]
	v_add_u32_e32 v104, s77, v192
	s_and_b64 vcc, vcc, s[42:43]
	v_add_u32_e32 v106, 10, v95
	v_cmp_eq_u32_e64 s[42:43], 0, v104
	v_cndmask_b32_e32 v171, v214, v171, vcc
	v_cmp_le_u32_e32 vcc, v106, v158
	s_or_b64 s[42:43], s[22:23], s[42:43]
	v_add_u32_e32 v104, s77, v191
	s_and_b64 vcc, vcc, s[42:43]
	v_add_u32_e32 v106, 11, v95
	v_cmp_eq_u32_e64 s[42:43], 0, v104
	v_cndmask_b32_e32 v168, v214, v168, vcc
	v_cmp_le_u32_e32 vcc, v106, v158
	s_or_b64 s[22:23], s[22:23], s[42:43]
	v_or_b32_e32 v106, 16, v95
	s_and_b64 vcc, vcc, s[22:23]
	v_or_b32_e32 v104, 17, v95
	v_cmp_lt_u32_e64 s[48:49], s11, v106
	v_cmp_eq_u32_e64 s[52:53], v106, v158
	v_cndmask_b32_e32 v169, v214, v169, vcc
	v_cmp_le_u32_e32 vcc, v106, v158
	v_cmp_lt_u32_e64 s[44:45], s11, v104
	v_cmp_eq_u32_e64 s[50:51], v104, v149
	s_or_b64 s[22:23], s[48:49], s[52:53]
	v_cmp_le_u32_e64 s[42:43], v104, v149
	s_or_b64 s[44:45], s[44:45], s[50:51]
	s_and_b64 vcc, vcc, s[22:23]
	v_or_b32_e32 v106, 18, v95
	v_cndmask_b32_e32 v102, v214, v102, vcc
	s_and_b64 vcc, s[42:43], s[44:45]
	v_or_b32_e32 v104, 19, v95
	v_cmp_lt_u32_e64 s[48:49], s11, v106
	v_cmp_eq_u32_e64 s[52:53], v106, v158
	v_cndmask_b32_e32 v103, v214, v103, vcc
	v_cmp_le_u32_e32 vcc, v106, v158
	v_cmp_lt_u32_e64 s[44:45], s11, v104
	v_cmp_eq_u32_e64 s[50:51], v104, v149
	s_or_b64 s[22:23], s[48:49], s[52:53]
	v_cmp_le_u32_e64 s[42:43], v104, v149
	s_or_b64 s[44:45], s[44:45], s[50:51]
	s_and_b64 vcc, vcc, s[22:23]
	v_or_b32_e32 v106, 24, v95
	v_cndmask_b32_e32 v100, v214, v100, vcc
	s_and_b64 vcc, s[42:43], s[44:45]
	v_or_b32_e32 v104, 25, v95
	v_cmp_lt_u32_e64 s[48:49], s11, v106
	v_cmp_eq_u32_e64 s[52:53], v106, v158
	v_cndmask_b32_e32 v101, v214, v101, vcc
	v_cmp_le_u32_e32 vcc, v106, v158
	v_cmp_lt_u32_e64 s[44:45], s11, v104
	v_cmp_eq_u32_e64 s[50:51], v104, v149
	s_or_b64 s[22:23], s[48:49], s[52:53]
	v_cmp_le_u32_e64 s[42:43], v104, v149
	s_or_b64 s[44:45], s[44:45], s[50:51]
	s_and_b64 vcc, vcc, s[22:23]
	v_or_b32_e32 v106, 26, v95
	v_cndmask_b32_e32 v98, v214, v98, vcc
	s_and_b64 vcc, s[42:43], s[44:45]
	v_or_b32_e32 v104, 27, v95
	v_cmp_lt_u32_e64 s[48:49], s11, v106
	v_cmp_eq_u32_e64 s[52:53], v106, v158
	v_cndmask_b32_e32 v99, v214, v99, vcc
	v_cmp_le_u32_e32 vcc, v106, v158
	v_cmp_lt_u32_e64 s[44:45], s11, v104
	v_cmp_eq_u32_e64 s[50:51], v104, v149
	s_or_b64 s[22:23], s[48:49], s[52:53]
	v_cmp_le_u32_e64 s[42:43], v104, v149
	s_or_b64 s[44:45], s[44:45], s[50:51]
	s_and_b64 vcc, vcc, s[22:23]
	v_cndmask_b32_e32 v96, v214, v96, vcc
	s_and_b64 vcc, s[42:43], s[44:45]
	v_add_u32_e32 v104, s77, v190
	v_add_u32_e32 v106, 32, v95
	v_cndmask_b32_e32 v97, v214, v97, vcc
	v_cmp_lt_u32_e32 vcc, s11, v106
	v_cmp_eq_u32_e64 s[42:43], 0, v104
	s_or_b64 s[22:23], vcc, s[42:43]
	v_cmp_le_u32_e32 vcc, v106, v158
	v_or_b32_e32 v106, 33, v95
	s_and_b64 vcc, vcc, s[22:23]
	v_or_b32_e32 v104, 34, v95
	v_cmp_lt_u32_e64 s[48:49], s11, v106
	v_cmp_eq_u32_e64 s[52:53], v106, v158
	v_cndmask_b32_e32 v105, v214, v105, vcc
	v_cmp_le_u32_e32 vcc, v106, v158
	v_cmp_lt_u32_e64 s[44:45], s11, v104
	v_cmp_eq_u32_e64 s[50:51], v104, v149
	s_or_b64 s[22:23], s[48:49], s[52:53]
	v_cmp_le_u32_e64 s[42:43], v104, v149
	s_or_b64 s[44:45], s[44:45], s[50:51]
	s_and_b64 vcc, vcc, s[22:23]
	v_or_b32_e32 v106, 35, v95
	v_cndmask_b32_e32 v80, v214, v80, vcc
	s_and_b64 vcc, s[42:43], s[44:45]
	v_or_b32_e32 v104, 40, v95
	v_cmp_lt_u32_e64 s[48:49], s11, v106
	v_cmp_eq_u32_e64 s[52:53], v106, v158
	v_cndmask_b32_e32 v81, v214, v81, vcc
	v_cmp_le_u32_e32 vcc, v106, v158
	v_cmp_lt_u32_e64 s[44:45], s11, v104
	v_cmp_eq_u32_e64 s[50:51], v104, v149
	s_or_b64 s[22:23], s[48:49], s[52:53]
	v_cmp_le_u32_e64 s[42:43], v104, v149
	s_or_b64 s[44:45], s[44:45], s[50:51]
	s_and_b64 vcc, vcc, s[22:23]
	v_or_b32_e32 v106, 41, v95
	v_cndmask_b32_e32 v82, v214, v82, vcc
	s_and_b64 vcc, s[42:43], s[44:45]
	v_or_b32_e32 v104, 42, v95
	v_cmp_lt_u32_e64 s[48:49], s11, v106
	v_cmp_eq_u32_e64 s[52:53], v106, v158
	v_cndmask_b32_e32 v83, v214, v83, vcc
	v_cmp_le_u32_e32 vcc, v106, v158
	v_cmp_lt_u32_e64 s[44:45], s11, v104
	v_cmp_eq_u32_e64 s[50:51], v104, v149
	s_or_b64 s[22:23], s[48:49], s[52:53]
	v_cmp_le_u32_e64 s[42:43], v104, v149
	s_or_b64 s[44:45], s[44:45], s[50:51]
	s_and_b64 vcc, vcc, s[22:23]
	v_or_b32_e32 v106, 43, v95
	v_cndmask_b32_e32 v84, v214, v84, vcc
	s_and_b64 vcc, s[42:43], s[44:45]
	v_or_b32_e32 v104, 48, v95
	v_cmp_lt_u32_e64 s[48:49], s11, v106
	v_cmp_eq_u32_e64 s[52:53], v106, v158
	v_cndmask_b32_e32 v85, v214, v85, vcc
	v_cmp_le_u32_e32 vcc, v106, v158
	v_cmp_lt_u32_e64 s[44:45], s11, v104
	v_cmp_eq_u32_e64 s[50:51], v104, v149
	s_or_b64 s[22:23], s[48:49], s[52:53]
	v_cmp_le_u32_e64 s[42:43], v104, v149
	s_or_b64 s[44:45], s[44:45], s[50:51]
	s_and_b64 vcc, vcc, s[22:23]
	v_or_b32_e32 v106, 49, v95
	v_cndmask_b32_e32 v86, v214, v86, vcc
	s_and_b64 vcc, s[42:43], s[44:45]
	v_or_b32_e32 v104, 50, v95
	v_cmp_lt_u32_e64 s[48:49], s11, v106
	v_cmp_eq_u32_e64 s[52:53], v106, v158
	v_cndmask_b32_e32 v87, v214, v87, vcc
	v_cmp_le_u32_e32 vcc, v106, v158
	v_cmp_lt_u32_e64 s[44:45], s11, v104
	v_cmp_eq_u32_e64 s[50:51], v104, v149
	s_or_b64 s[22:23], s[48:49], s[52:53]
	v_cmp_le_u32_e64 s[42:43], v104, v149
	s_or_b64 s[44:45], s[44:45], s[50:51]
	s_and_b64 vcc, vcc, s[22:23]
	v_or_b32_e32 v106, 51, v95
	v_cndmask_b32_e32 v88, v214, v88, vcc
	s_and_b64 vcc, s[42:43], s[44:45]
	v_or_b32_e32 v104, 56, v95
	v_cmp_lt_u32_e64 s[48:49], s11, v106
	v_cmp_eq_u32_e64 s[52:53], v106, v158
	v_cndmask_b32_e32 v89, v214, v89, vcc
	v_cmp_le_u32_e32 vcc, v106, v158
	v_cmp_lt_u32_e64 s[44:45], s11, v104
	v_cmp_eq_u32_e64 s[50:51], v104, v149
	s_or_b64 s[22:23], s[48:49], s[52:53]
	v_cmp_le_u32_e64 s[42:43], v104, v149
	s_or_b64 s[44:45], s[44:45], s[50:51]
	s_and_b64 vcc, vcc, s[22:23]
	v_or_b32_e32 v106, 57, v95
	v_cndmask_b32_e32 v90, v214, v90, vcc
	s_and_b64 vcc, s[42:43], s[44:45]
	v_or_b32_e32 v104, 58, v95
	v_cmp_lt_u32_e64 s[48:49], s11, v106
	v_cmp_eq_u32_e64 s[52:53], v106, v158
	v_cndmask_b32_e32 v91, v214, v91, vcc
	v_cmp_le_u32_e32 vcc, v106, v158
	v_cmp_lt_u32_e64 s[44:45], s11, v104
	v_cmp_eq_u32_e64 s[50:51], v104, v149
	s_or_b64 s[22:23], s[48:49], s[52:53]
	v_cmp_le_u32_e64 s[42:43], v104, v149
	s_or_b64 s[44:45], s[44:45], s[50:51]
	s_and_b64 vcc, vcc, s[22:23]
	v_add_u32_e32 v104, s77, v189
	v_add_u32_e32 v95, 59, v95
	v_cndmask_b32_e32 v92, v214, v92, vcc
	s_and_b64 vcc, s[42:43], s[44:45]
	v_cmp_lt_u32_e64 s[42:43], s11, v95
	v_cmp_eq_u32_e64 s[44:45], 0, v104
	v_cndmask_b32_e32 v93, v214, v93, vcc
	v_cmp_le_u32_e32 vcc, v95, v158
	s_or_b64 s[22:23], s[42:43], s[44:45]
	s_and_b64 vcc, vcc, s[22:23]
	v_cndmask_b32_e32 v94, v214, v94, vcc

.LBB0_388:
	s_mul_i32 s13, s40, 0x4400
	v_add_u32_e32 v0, s13, v144
	ds_read_b128 v[2:5], v0
	ds_read_b128 v[6:9], v0 offset:32
	ds_read_b128 v[10:13], v0 offset:64
	ds_read_b128 v[162:165], v0 offset:96
	ds_read_b128 v[80:83], v0 offset:8704
	ds_read_b128 v[184:187], v0 offset:8736
	ds_read_b128 v[188:191], v0 offset:8768
	ds_read_b128 v[192:195], v0 offset:8800
	s_waitcnt lgkmcnt(0)
	s_add_i32 s68, s23, s22
	s_waitcnt lgkmcnt(7)
	v_mfma_f32_32x32x16_bf16 v[96:111], v[2:5], v[112:115], 0
	s_cmp_ge_u32 s67, s66
	s_cselect_b64 s[42:43], -1, 0
	s_cmp_lt_u32 s67, 2
	s_cselect_b64 s[44:45], -1, 0
	s_or_b64 s[42:43], s[44:45], s[42:43]
	s_andn2_b64 vcc, exec, s[42:43]
	s_waitcnt lgkmcnt(3)
	v_mfma_f32_32x32x16_bf16 v[80:95], v[80:83], v[112:115], 0
	v_mfma_f32_32x32x16_bf16 v[96:111], v[6:9], v[116:119], v[96:111]
	s_waitcnt lgkmcnt(2)
	v_mfma_f32_32x32x16_bf16 v[80:95], v[184:187], v[116:119], v[80:95]
	v_mfma_f32_32x32x16_bf16 v[96:111], v[10:13], v[120:123], v[96:111]
	s_waitcnt lgkmcnt(1)
	v_mfma_f32_32x32x16_bf16 v[80:95], v[188:191], v[120:123], v[80:95]
	v_mfma_f32_32x32x16_bf16 v[96:111], v[162:165], v[124:127], v[96:111]
	s_waitcnt lgkmcnt(0)
	v_mfma_f32_32x32x16_bf16 v[80:95], v[192:195], v[124:127], v[80:95]
	s_nop 9
	v_mul_f32_e64 v164, v98, s24
	v_mul_f32_e64 v165, v99, s24
	v_mul_f32_e64 v98, v100, s24
	v_mul_f32_e64 v99, v101, s24
	v_mul_f32_e64 v162, v96, s24
	v_mul_f32_e64 v163, v97, s24
	v_pk_mul_f32 v[96:97], v[102:103], s[24:25] op_sel_hi:[1,0]
	v_pk_mul_f32 v[12:13], v[104:105], s[24:25] op_sel_hi:[1,0]
	v_pk_mul_f32 v[8:9], v[106:107], s[24:25] op_sel_hi:[1,0]
	v_pk_mul_f32 v[4:5], v[108:109], s[24:25] op_sel_hi:[1,0]
	v_mul_f32_e32 v100, 0x3e38aa3b, v80
	v_pk_mul_f32 v[2:3], v[110:111], s[24:25] op_sel_hi:[1,0]
	v_mul_f32_e32 v6, 0x3e38aa3b, v81
	v_mul_f32_e32 v7, 0x3e38aa3b, v82
	v_mul_f32_e32 v10, 0x3e38aa3b, v83
	v_mul_f32_e32 v11, 0x3e38aa3b, v84
	v_mul_f32_e32 v14, 0x3e38aa3b, v85
	v_mul_f32_e32 v15, 0x3e38aa3b, v86
	v_mul_f32_e32 v80, 0x3e38aa3b, v87
	v_mul_f32_e32 v81, 0x3e38aa3b, v88
	v_mul_f32_e32 v82, 0x3e38aa3b, v89
	v_mul_f32_e32 v83, 0x3e38aa3b, v90
	v_mul_f32_e32 v84, 0x3e38aa3b, v91
	v_mul_f32_e32 v85, 0x3e38aa3b, v92
	v_mul_f32_e32 v86, 0x3e38aa3b, v93
	v_mul_f32_e32 v87, 0x3e38aa3b, v94
	v_mul_f32_e32 v88, 0x3e38aa3b, v95
	s_cbranch_vccnz .LBB0_390
	s_cmpk_gt_u32 s68, 0x6f
	v_add_u32_e32 v0, s22, v166
	s_cselect_b64 s[44:45], -1, 0
	v_cmp_eq_u32_e32 vcc, s22, v182
	s_or_b64 s[42:43], s[44:45], vcc
	v_cmp_le_u32_e32 vcc, v0, v158
	v_add_u32_e32 v89, s22, v175
	s_and_b64 vcc, vcc, s[42:43]
	v_cmp_eq_u32_e64 s[42:43], 0, v89
	v_cndmask_b32_e32 v162, v214, v162, vcc
	v_cmp_lt_u32_e32 vcc, v0, v158
	s_or_b64 s[42:43], s[44:45], s[42:43]
	v_add_u32_e32 v89, s22, v174
	s_and_b64 vcc, vcc, s[42:43]
	v_add_u32_e32 v90, 2, v0
	v_cmp_eq_u32_e64 s[42:43], 0, v89
	v_cndmask_b32_e32 v163, v214, v163, vcc
	v_cmp_le_u32_e32 vcc, v90, v158
	s_or_b64 s[42:43], s[44:45], s[42:43]
	v_add_u32_e32 v89, s22, v173
	s_and_b64 vcc, vcc, s[42:43]
	v_add_u32_e32 v90, 3, v0
	v_cmp_eq_u32_e64 s[42:43], 0, v89
	v_cndmask_b32_e32 v164, v214, v164, vcc
	v_cmp_le_u32_e32 vcc, v90, v158
	s_or_b64 s[42:43], s[44:45], s[42:43]
	v_add_u32_e32 v89, s22, v172
	s_and_b64 vcc, vcc, s[42:43]
	v_add_u32_e32 v90, 8, v0
	v_cmp_eq_u32_e64 s[42:43], 0, v89
	v_cndmask_b32_e32 v165, v214, v165, vcc
	v_cmp_le_u32_e32 vcc, v90, v158
	s_or_b64 s[42:43], s[44:45], s[42:43]
	v_add_u32_e32 v89, s22, v171
	s_and_b64 vcc, vcc, s[42:43]
	v_add_u32_e32 v90, 9, v0
	v_cmp_eq_u32_e64 s[42:43], 0, v89
	v_cndmask_b32_e32 v98, v214, v98, vcc
	v_cmp_le_u32_e32 vcc, v90, v158
	s_or_b64 s[42:43], s[44:45], s[42:43]
	v_add_u32_e32 v89, s22, v170
	s_and_b64 vcc, vcc, s[42:43]
	v_add_u32_e32 v90, 10, v0
	v_cmp_eq_u32_e64 s[42:43], 0, v89
	v_cndmask_b32_e32 v99, v214, v99, vcc
	v_cmp_le_u32_e32 vcc, v90, v158
	s_or_b64 s[42:43], s[44:45], s[42:43]
	v_add_u32_e32 v89, s22, v169
	s_and_b64 vcc, vcc, s[42:43]
	v_add_u32_e32 v90, 11, v0
	v_cmp_eq_u32_e64 s[42:43], 0, v89
	v_cndmask_b32_e32 v96, v214, v96, vcc
	v_cmp_le_u32_e32 vcc, v90, v158
	s_or_b64 s[42:43], s[44:45], s[42:43]
	v_or_b32_e32 v90, 16, v0
	s_and_b64 vcc, vcc, s[42:43]
	v_or_b32_e32 v89, 17, v0
	v_cmp_lt_u32_e64 s[48:49], s11, v90
	v_cmp_eq_u32_e64 s[52:53], v90, v158
	v_cndmask_b32_e32 v97, v214, v97, vcc
	v_cmp_le_u32_e32 vcc, v90, v158
	v_cmp_lt_u32_e64 s[44:45], s11, v89
	v_cmp_eq_u32_e64 s[50:51], v89, v145
	s_or_b64 s[48:49], s[48:49], s[52:53]
	v_cmp_le_u32_e64 s[42:43], v89, v145
	s_or_b64 s[44:45], s[44:45], s[50:51]
	s_and_b64 vcc, vcc, s[48:49]
	v_or_b32_e32 v90, 18, v0
	v_cndmask_b32_e32 v12, v214, v12, vcc
	s_and_b64 vcc, s[42:43], s[44:45]
	v_or_b32_e32 v89, 19, v0
	v_cmp_lt_u32_e64 s[48:49], s11, v90
	v_cmp_eq_u32_e64 s[52:53], v90, v158
	v_cndmask_b32_e32 v13, v214, v13, vcc
	v_cmp_le_u32_e32 vcc, v90, v158
	v_cmp_lt_u32_e64 s[44:45], s11, v89
	v_cmp_eq_u32_e64 s[50:51], v89, v145
	s_or_b64 s[48:49], s[48:49], s[52:53]
	v_cmp_le_u32_e64 s[42:43], v89, v145
	s_or_b64 s[44:45], s[44:45], s[50:51]
	s_and_b64 vcc, vcc, s[48:49]
	v_or_b32_e32 v90, 24, v0
	v_cndmask_b32_e32 v8, v214, v8, vcc
	s_and_b64 vcc, s[42:43], s[44:45]
	v_or_b32_e32 v89, 25, v0
	v_cmp_lt_u32_e64 s[48:49], s11, v90
	v_cmp_eq_u32_e64 s[52:53], v90, v158
	v_cndmask_b32_e32 v9, v214, v9, vcc
	v_cmp_le_u32_e32 vcc, v90, v158
	v_cmp_lt_u32_e64 s[44:45], s11, v89
	v_cmp_eq_u32_e64 s[50:51], v89, v145
	s_or_b64 s[48:49], s[48:49], s[52:53]
	v_cmp_le_u32_e64 s[42:43], v89, v145
	s_or_b64 s[44:45], s[44:45], s[50:51]
	s_and_b64 vcc, vcc, s[48:49]
	v_or_b32_e32 v90, 26, v0
	v_cndmask_b32_e32 v4, v214, v4, vcc
	s_and_b64 vcc, s[42:43], s[44:45]
	v_or_b32_e32 v89, 27, v0
	v_cmp_lt_u32_e64 s[48:49], s11, v90
	v_cmp_eq_u32_e64 s[52:53], v90, v158
	v_cndmask_b32_e32 v5, v214, v5, vcc
	v_cmp_le_u32_e32 vcc, v90, v158
	v_cmp_lt_u32_e64 s[44:45], s11, v89
	v_cmp_eq_u32_e64 s[50:51], v89, v145
	s_or_b64 s[48:49], s[48:49], s[52:53]
	v_cmp_le_u32_e64 s[42:43], v89, v145
	s_or_b64 s[44:45], s[44:45], s[50:51]
	s_and_b64 vcc, vcc, s[48:49]
	v_cndmask_b32_e32 v2, v214, v2, vcc
	s_and_b64 vcc, s[42:43], s[44:45]
	v_add_u32_e32 v89, s22, v168
	v_add_u32_e32 v90, 32, v0
	v_cndmask_b32_e32 v3, v214, v3, vcc
	v_cmp_lt_u32_e32 vcc, s11, v90
	v_cmp_eq_u32_e64 s[42:43], 0, v89
	s_or_b64 s[42:43], vcc, s[42:43]
	v_cmp_le_u32_e32 vcc, v90, v158
	v_or_b32_e32 v90, 33, v0
	s_and_b64 vcc, vcc, s[42:43]
	v_or_b32_e32 v89, 34, v0
	v_cmp_lt_u32_e64 s[48:49], s11, v90
	v_cmp_eq_u32_e64 s[52:53], v90, v158
	v_cndmask_b32_e32 v100, v214, v100, vcc
	v_cmp_le_u32_e32 vcc, v90, v158
	v_cmp_lt_u32_e64 s[44:45], s11, v89
	v_cmp_eq_u32_e64 s[50:51], v89, v145
	s_or_b64 s[48:49], s[48:49], s[52:53]
	v_cmp_le_u32_e64 s[42:43], v89, v145
	s_or_b64 s[44:45], s[44:45], s[50:51]
	s_and_b64 vcc, vcc, s[48:49]
	v_or_b32_e32 v90, 35, v0
	v_cndmask_b32_e32 v6, v214, v6, vcc
	s_and_b64 vcc, s[42:43], s[44:45]
	v_or_b32_e32 v89, 40, v0
	v_cmp_lt_u32_e64 s[48:49], s11, v90
	v_cmp_eq_u32_e64 s[52:53], v90, v158
	v_cndmask_b32_e32 v7, v214, v7, vcc
	v_cmp_le_u32_e32 vcc, v90, v158
	v_cmp_lt_u32_e64 s[44:45], s11, v89
	v_cmp_eq_u32_e64 s[50:51], v89, v145
	s_or_b64 s[48:49], s[48:49], s[52:53]
	v_cmp_le_u32_e64 s[42:43], v89, v145
	s_or_b64 s[44:45], s[44:45], s[50:51]
	s_and_b64 vcc, vcc, s[48:49]
	v_or_b32_e32 v90, 41, v0
	v_cndmask_b32_e32 v10, v214, v10, vcc
	s_and_b64 vcc, s[42:43], s[44:45]
	v_or_b32_e32 v89, 42, v0
	v_cmp_lt_u32_e64 s[48:49], s11, v90
	v_cmp_eq_u32_e64 s[52:53], v90, v158
	v_cndmask_b32_e32 v11, v214, v11, vcc
	v_cmp_le_u32_e32 vcc, v90, v158
	v_cmp_lt_u32_e64 s[44:45], s11, v89
	v_cmp_eq_u32_e64 s[50:51], v89, v145
	s_or_b64 s[48:49], s[48:49], s[52:53]
	v_cmp_le_u32_e64 s[42:43], v89, v145
	s_or_b64 s[44:45], s[44:45], s[50:51]
	s_and_b64 vcc, vcc, s[48:49]
	v_or_b32_e32 v90, 43, v0
	v_cndmask_b32_e32 v14, v214, v14, vcc
	s_and_b64 vcc, s[42:43], s[44:45]
	v_or_b32_e32 v89, 48, v0
	v_cmp_lt_u32_e64 s[48:49], s11, v90
	v_cmp_eq_u32_e64 s[52:53], v90, v158
	v_cndmask_b32_e32 v15, v214, v15, vcc
	v_cmp_le_u32_e32 vcc, v90, v158
	v_cmp_lt_u32_e64 s[44:45], s11, v89
	v_cmp_eq_u32_e64 s[50:51], v89, v145
	s_or_b64 s[48:49], s[48:49], s[52:53]
	v_cmp_le_u32_e64 s[42:43], v89, v145
	s_or_b64 s[44:45], s[44:45], s[50:51]
	s_and_b64 vcc, vcc, s[48:49]
	v_or_b32_e32 v90, 49, v0
	v_cndmask_b32_e32 v80, v214, v80, vcc
	s_and_b64 vcc, s[42:43], s[44:45]
	v_or_b32_e32 v89, 50, v0
	v_cmp_lt_u32_e64 s[48:49], s11, v90
	v_cmp_eq_u32_e64 s[52:53], v90, v158
	v_cndmask_b32_e32 v81, v214, v81, vcc
	v_cmp_le_u32_e32 vcc, v90, v158
	v_cmp_lt_u32_e64 s[44:45], s11, v89
	v_cmp_eq_u32_e64 s[50:51], v89, v145
	s_or_b64 s[48:49], s[48:49], s[52:53]
	v_cmp_le_u32_e64 s[42:43], v89, v145
	s_or_b64 s[44:45], s[44:45], s[50:51]
	s_and_b64 vcc, vcc, s[48:49]
	v_or_b32_e32 v90, 51, v0
	v_cndmask_b32_e32 v82, v214, v82, vcc
	s_and_b64 vcc, s[42:43], s[44:45]
	v_or_b32_e32 v89, 56, v0
	v_cmp_lt_u32_e64 s[48:49], s11, v90
	v_cmp_eq_u32_e64 s[52:53], v90, v158
	v_cndmask_b32_e32 v83, v214, v83, vcc
	v_cmp_le_u32_e32 vcc, v90, v158
	v_cmp_lt_u32_e64 s[44:45], s11, v89
	v_cmp_eq_u32_e64 s[50:51], v89, v145
	s_or_b64 s[48:49], s[48:49], s[52:53]
	v_cmp_le_u32_e64 s[42:43], v89, v145
	s_or_b64 s[44:45], s[44:45], s[50:51]
	s_and_b64 vcc, vcc, s[48:49]
	v_or_b32_e32 v90, 57, v0
	v_cndmask_b32_e32 v84, v214, v84, vcc
	s_and_b64 vcc, s[42:43], s[44:45]
	v_or_b32_e32 v89, 58, v0
	v_cmp_lt_u32_e64 s[48:49], s11, v90
	v_cmp_eq_u32_e64 s[52:53], v90, v158
	v_cndmask_b32_e32 v85, v214, v85, vcc
	v_cmp_le_u32_e32 vcc, v90, v158
	v_cmp_lt_u32_e64 s[44:45], s11, v89
	v_cmp_eq_u32_e64 s[50:51], v89, v145
	s_or_b64 s[48:49], s[48:49], s[52:53]
	v_cmp_le_u32_e64 s[42:43], v89, v145
	s_or_b64 s[44:45], s[44:45], s[50:51]
	s_and_b64 vcc, vcc, s[48:49]
	v_add_u32_e32 v89, s22, v167
	v_add_u32_e32 v0, 59, v0
	v_cndmask_b32_e32 v86, v214, v86, vcc
	s_and_b64 vcc, s[42:43], s[44:45]
	v_cmp_lt_u32_e64 s[42:43], s11, v0
	v_cmp_eq_u32_e64 s[44:45], 0, v89
	v_cndmask_b32_e32 v87, v214, v87, vcc
	v_cmp_le_u32_e32 vcc, v0, v158
	s_or_b64 s[42:43], s[42:43], s[44:45]
	s_and_b64 vcc, vcc, s[42:43]
	v_cndmask_b32_e32 v88, v214, v88, vcc

.LBB0_723:
	s_ashr_i32 s49, s48, 31
	s_lshl_b64 s[8:9], s[48:49], 21
	s_add_u32 s52, s44, s8
	s_addc_u32 s53, s45, s9
	s_and_b64 s[0:1], s[0:1], exec
	s_cselect_b32 s49, s53, s7
	s_cselect_b32 s80, s52, s6
	s_lshr_b32 s0, s22, 3
	s_mulk_i32 s0, 0x880
	s_lshl_b32 s1, s22, 8
	s_and_b32 s1, s1, 0x700
	s_add_i32 s82, s64, s0
	s_lshl_b32 s81, s14, 8
	s_add_i32 s82, s82, s1
	s_or_b32 s83, s81, s75
	s_add_u32 s0, s12, 0x100
	s_addc_u32 s1, s13, 0
	s_add_u32 s8, s6, 0x100
	s_addc_u32 s9, s7, 0
	s_add_u32 s6, s12, 0x100080
	s_addc_u32 s7, s13, 0
	v_mov_b64_e32 v[2:3], 0
	v_lshl_add_u64 v[156:157], s[6:7], 0, v[144:145]
	v_lshl_add_u64 v[158:159], s[6:7], 0, v[146:147]
	s_mov_b32 s14, 0
	s_mov_b64 s[26:27], -1
	s_mov_b64 s[6:7], 0
	v_mov_b64_e32 v[4:5], 0
	v_mov_b64_e32 v[6:7], 0
	v_mov_b64_e32 v[8:9], 0
	v_mov_b64_e32 v[10:11], 0
	v_mov_b64_e32 v[12:13], 0
	v_mov_b64_e32 v[14:15], 0
	v_mov_b64_e32 v[16:17], 0
	v_mov_b64_e32 v[18:19], 0
	v_mov_b64_e32 v[20:21], 0
	v_mov_b64_e32 v[22:23], 0
	v_mov_b64_e32 v[24:25], 0
	v_mov_b64_e32 v[26:27], 0
	v_mov_b64_e32 v[28:29], 0
	v_mov_b64_e32 v[30:31], 0
	v_mov_b64_e32 v[32:33], 0
	v_mov_b64_e32 v[34:35], 0
	v_mov_b64_e32 v[36:37], 0
	v_mov_b64_e32 v[38:39], 0
	v_mov_b64_e32 v[40:41], 0
	v_mov_b64_e32 v[42:43], 0
	v_mov_b64_e32 v[44:45], 0
	v_mov_b64_e32 v[46:47], 0
	v_mov_b64_e32 v[48:49], 0
	v_mov_b64_e32 v[50:51], 0
	v_mov_b64_e32 v[52:53], 0
	v_mov_b64_e32 v[54:55], 0
	v_mov_b64_e32 v[56:57], 0
	v_mov_b64_e32 v[58:59], 0
	v_mov_b64_e32 v[60:61], 0
	v_mov_b64_e32 v[62:63], 0
	v_mov_b64_e32 v[64:65], 0
	v_mov_b64_e32 v[66:67], 0
	v_mov_b64_e32 v[68:69], 0
	v_mov_b64_e32 v[70:71], 0
	v_mov_b64_e32 v[72:73], 0
	v_mov_b64_e32 v[74:75], 0
	v_mov_b64_e32 v[76:77], 0
	v_mov_b64_e32 v[78:79], 0
	v_mov_b64_e32 v[80:81], 0
	v_mov_b64_e32 v[82:83], 0
	v_mov_b64_e32 v[84:85], 0
	v_mov_b64_e32 v[86:87], 0
	v_mov_b64_e32 v[88:89], 0
	v_mov_b64_e32 v[90:91], 0
	v_mov_b64_e32 v[92:93], 0
	v_mov_b64_e32 v[94:95], 0
	v_mov_b64_e32 v[96:97], 0
	v_mov_b64_e32 v[98:99], 0
	v_mov_b64_e32 v[100:101], 0
	v_mov_b64_e32 v[102:103], 0
	v_mov_b64_e32 v[104:105], 0
	v_mov_b64_e32 v[106:107], 0
	v_mov_b64_e32 v[108:109], 0
	v_mov_b64_e32 v[110:111], 0
	v_mov_b64_e32 v[112:113], 0
	v_mov_b64_e32 v[114:115], 0
	v_mov_b64_e32 v[116:117], 0
	v_mov_b64_e32 v[118:119], 0
	v_mov_b64_e32 v[120:121], 0
	v_mov_b64_e32 v[122:123], 0
	v_mov_b64_e32 v[124:125], 0
	v_mov_b64_e32 v[126:127], 0
	v_mov_b64_e32 v[128:129], 0

.LBB0_795:
	v_lshl_add_u64 v[12:13], s[26:27], 0, v[0:1]
	v_mov_b32_e32 v135, v1
	s_and_b32 s65, s1, 3
	v_and_b32_e32 v11, 48, v2
	v_lshlrev_b32_e32 v20, 6, v2
	s_movk_i32 s1, 0x3c0
	v_lshlrev_b32_e32 v2, 2, v2
	v_lshl_add_u64 v[14:15], s[26:27], 0, v[134:135]
	s_lshl_b32 s66, s0, 6
	s_lshl_b32 s0, s0, 13
	v_and_or_b32 v11, v20, s1, v11
	v_and_b32_e32 v2, 32, v2
	s_add_i32 m0, s61, 0x18000
	v_lshl_add_u64 v[12:13], v[12:13], 0, s[16:17]
	v_lshl_add_u64 v[16:17], s[6:7], 0, v[0:1]
	v_bitop3_b32 v20, v11, s0, v2 bitop3:0xde
	s_lshl_b32 s0, s65, 12
	s_waitcnt vmcnt(4)
	s_barrier
	global_load_lds_dwordx4 v[12:13], off
	v_lshl_add_u64 v[12:13], v[14:15], 0, s[16:17]
	s_add_i32 m0, s61, 0x1a000
	s_add_i32 s69, s61, 0x8000
	s_add_i32 s75, s61, 0xa000
	v_lshl_add_u64 v[18:19], s[6:7], 0, v[134:135]
	v_bitop3_b32 v144, v11, s0, v2 bitop3:0xde
	global_load_lds_dwordx4 v[12:13], off
	v_lshl_add_u64 v[12:13], v[16:17], 0, s[16:17]
	s_mov_b32 m0, s69
	s_add_u32 s0, s26, 0x80080
	global_load_lds_dwordx4 v[12:13], off
	v_lshl_add_u64 v[12:13], v[18:19], 0, s[16:17]
	s_mov_b32 m0, s75
	s_addc_u32 s1, s27, 0
	global_load_lds_dwordx4 v[12:13], off
	s_add_i32 m0, s61, 0x1c000
	v_lshl_add_u64 v[12:13], s[0:1], 0, v[0:1]
	global_load_lds_dwordx4 v[12:13], off
	v_lshl_add_u64 v[12:13], s[0:1], 0, v[134:135]
	s_add_i32 m0, s61, 0x1e000
	v_lshlrev_b32_e32 v2, 14, v8
	global_load_lds_dwordx4 v[12:13], off
	v_and_b32_e32 v2, 0x7fff8000, v2
	v_lshl_add_u32 v2, v7, 11, v2
	v_or_b32_e32 v2, v2, v9
	v_add_lshl_u32 v136, v2, v10, 1
	v_lshlrev_b32_e32 v2, 14, v3
	v_and_b32_e32 v2, 0x7fff8000, v2
	v_lshl_add_u32 v2, v4, 11, v2
	s_waitcnt vmcnt(6)
	v_or_b32_e32 v2, v2, v5
	v_add_lshl_u32 v138, v2, v6, 1
	v_mov_b64_e32 v[2:3], 0
	v_readlane_b32 s0, v254, 50
	v_mov_b32_e32 v137, v1
	v_mov_b32_e32 v139, v1
	s_mov_b32 s76, 0
	v_add_u32_e32 v145, 0, v20
	v_readlane_b32 s14, v254, 58
	s_mov_b32 s50, s0
	v_mov_b64_e32 v[4:5], 0
	v_mov_b64_e32 v[6:7], 0
	v_mov_b64_e32 v[8:9], 0
	v_mov_b64_e32 v[10:11], 0
	v_mov_b64_e32 v[12:13], 0
	v_mov_b64_e32 v[14:15], 0
	v_mov_b64_e32 v[16:17], 0
	v_mov_b64_e32 v[18:19], 0
	v_mov_b64_e32 v[20:21], 0
	v_mov_b64_e32 v[22:23], 0
	v_mov_b64_e32 v[24:25], 0
	v_mov_b64_e32 v[26:27], 0
	v_mov_b64_e32 v[28:29], 0
	v_mov_b64_e32 v[30:31], 0
	v_mov_b64_e32 v[32:33], 0
	v_mov_b64_e32 v[34:35], 0
	v_mov_b64_e32 v[36:37], 0
	v_mov_b64_e32 v[38:39], 0
	v_mov_b64_e32 v[40:41], 0
	v_mov_b64_e32 v[42:43], 0
	v_mov_b64_e32 v[44:45], 0
	v_mov_b64_e32 v[46:47], 0
	v_mov_b64_e32 v[48:49], 0
	v_mov_b64_e32 v[50:51], 0
	v_mov_b64_e32 v[52:53], 0
	v_mov_b64_e32 v[54:55], 0
	v_mov_b64_e32 v[56:57], 0
	v_mov_b64_e32 v[58:59], 0
	v_mov_b64_e32 v[60:61], 0
	v_mov_b64_e32 v[62:63], 0
	v_mov_b64_e32 v[64:65], 0
	v_mov_b64_e32 v[66:67], 0
	v_mov_b64_e32 v[68:69], 0
	v_mov_b64_e32 v[70:71], 0
	v_mov_b64_e32 v[72:73], 0
	v_mov_b64_e32 v[74:75], 0
	v_mov_b64_e32 v[76:77], 0
	v_mov_b64_e32 v[78:79], 0
	v_mov_b64_e32 v[80:81], 0
	v_mov_b64_e32 v[82:83], 0
	v_mov_b64_e32 v[84:85], 0
	v_mov_b64_e32 v[86:87], 0
	v_mov_b64_e32 v[88:89], 0
	v_mov_b64_e32 v[90:91], 0
	v_mov_b64_e32 v[92:93], 0
	v_mov_b64_e32 v[94:95], 0
	v_mov_b64_e32 v[96:97], 0
	v_mov_b64_e32 v[98:99], 0
	v_mov_b64_e32 v[100:101], 0
	v_mov_b64_e32 v[102:103], 0
	v_mov_b64_e32 v[104:105], 0
	v_mov_b64_e32 v[106:107], 0
	v_mov_b64_e32 v[108:109], 0
	v_mov_b64_e32 v[110:111], 0
	v_mov_b64_e32 v[112:113], 0
	v_mov_b64_e32 v[114:115], 0
	v_mov_b64_e32 v[116:117], 0
	v_mov_b64_e32 v[118:119], 0
	v_mov_b64_e32 v[120:121], 0
	v_mov_b64_e32 v[122:123], 0
	v_mov_b64_e32 v[124:125], 0
	v_mov_b64_e32 v[126:127], 0
	v_mov_b64_e32 v[128:129], 0
	s_barrier
	s_branch .LBB0_798

.LBB0_807:
	s_add_u32 s30, s6, s26
	s_addc_u32 s31, s7, s27
	s_add_u32 s30, s30, 0x100
	s_addc_u32 s31, s31, 0
	s_add_u32 s81, s79, s26
	s_addc_u32 s82, s80, s27
	s_add_i32 s83, 0, 0x10000
	ds_read_b128 v[152:155], v224
	ds_read_b128 v[156:159], v224 offset:1024
	ds_read_b128 v[160:163], v224 offset:2048
	ds_read_b128 v[164:167], v224 offset:3072
	s_cmpk_eq_i32 s26, 0xf00
	s_cselect_b32 s41, s23, s31
	s_cselect_b32 s40, s22, s30
	s_cselect_b32 s31, s9, s82
	s_cselect_b32 s30, s44, s81
	v_lshl_add_u64 v[146:147], v[140:141], 0, s[26:27]
	s_add_i32 m0, s61, 0xc000
	ds_read_b128 v[168:171], v145
	ds_read_b128 v[172:175], v145 offset:1024
	ds_read_b128 v[176:179], v145 offset:2048
	ds_read_b128 v[180:183], v145 offset:3072
	ds_read_b128 v[184:187], v145 offset:4096
	ds_read_b128 v[188:191], v145 offset:5120
	ds_read_b128 v[192:195], v145 offset:6144
	ds_read_b128 v[196:199], v145 offset:7168
	global_load_lds_dwordx4 v[146:147], off
	v_lshl_add_u64 v[146:147], v[142:143], 0, s[26:27]
	s_add_i32 m0, s61, 0xe000
	s_nop 0
	global_load_lds_dwordx4 v[146:147], off
	s_waitcnt lgkmcnt(8)
	s_barrier
	s_waitcnt lgkmcnt(7)
	v_mfma_f32_16x16x32_bf16 v[126:129], v[152:155], v[168:171], v[126:129]
	v_mfma_f32_16x16x32_bf16 v[122:125], v[160:163], v[168:171], v[122:125]
	s_waitcnt lgkmcnt(5)
	v_mfma_f32_16x16x32_bf16 v[110:113], v[152:155], v[176:179], v[110:113]
	v_mfma_f32_16x16x32_bf16 v[106:109], v[160:163], v[176:179], v[106:109]
	s_waitcnt lgkmcnt(3)
	v_mfma_f32_16x16x32_bf16 v[94:97], v[152:155], v[184:187], v[94:97]
	v_mfma_f32_16x16x32_bf16 v[90:93], v[160:163], v[184:187], v[90:93]
	s_waitcnt lgkmcnt(1)
	v_mfma_f32_16x16x32_bf16 v[78:81], v[152:155], v[192:195], v[78:81]
	v_mfma_f32_16x16x32_bf16 v[74:77], v[160:163], v[192:195], v[74:77]
	v_mfma_f32_16x16x32_bf16 v[126:129], v[156:159], v[172:175], v[126:129]
	v_mfma_f32_16x16x32_bf16 v[122:125], v[164:167], v[172:175], v[122:125]
	v_mfma_f32_16x16x32_bf16 v[110:113], v[156:159], v[180:183], v[110:113]
	v_mfma_f32_16x16x32_bf16 v[106:109], v[164:167], v[180:183], v[106:109]
	v_mfma_f32_16x16x32_bf16 v[94:97], v[156:159], v[188:191], v[94:97]
	v_mfma_f32_16x16x32_bf16 v[90:93], v[164:167], v[188:191], v[90:93]
	s_waitcnt lgkmcnt(0)
	v_mfma_f32_16x16x32_bf16 v[78:81], v[156:159], v[196:199], v[78:81]
	v_mfma_f32_16x16x32_bf16 v[74:77], v[164:167], v[196:199], v[74:77]
	s_barrier
	s_add_i32 s81, 0, 0x14000
	s_add_i32 s82, s83, s60
	ds_read_b128 v[200:203], v225
	ds_read_b128 v[204:207], v225 offset:1024
	ds_read_b128 v[216:219], v225 offset:2048
	ds_read_b128 v[220:223], v225 offset:3072
	s_mov_b32 m0, s82
	s_nop 0
	global_load_lds_dwordx4 v0, s[30:31]
	s_add_i32 m0, s82, 0x2000
	s_nop 0
	global_load_lds_dwordx4 v134, s[30:31]
	s_barrier
	s_waitcnt lgkmcnt(3)
	v_mfma_f32_16x16x32_bf16 v[118:121], v[200:203], v[168:171], v[118:121]
	s_waitcnt lgkmcnt(1)
	v_mfma_f32_16x16x32_bf16 v[114:117], v[216:219], v[168:171], v[114:117]
	v_mfma_f32_16x16x32_bf16 v[102:105], v[200:203], v[176:179], v[102:105]
	v_mfma_f32_16x16x32_bf16 v[98:101], v[216:219], v[176:179], v[98:101]
	v_mfma_f32_16x16x32_bf16 v[86:89], v[200:203], v[184:187], v[86:89]
	v_mfma_f32_16x16x32_bf16 v[82:85], v[216:219], v[184:187], v[82:85]
	v_mfma_f32_16x16x32_bf16 v[70:73], v[200:203], v[192:195], v[70:73]
	v_mfma_f32_16x16x32_bf16 v[66:69], v[216:219], v[192:195], v[66:69]
	v_mfma_f32_16x16x32_bf16 v[118:121], v[204:207], v[172:175], v[118:121]
	s_waitcnt lgkmcnt(0)
	v_mfma_f32_16x16x32_bf16 v[114:117], v[220:223], v[172:175], v[114:117]
	v_mfma_f32_16x16x32_bf16 v[102:105], v[204:207], v[180:183], v[102:105]
	v_mfma_f32_16x16x32_bf16 v[98:101], v[220:223], v[180:183], v[98:101]
	v_mfma_f32_16x16x32_bf16 v[86:89], v[204:207], v[188:191], v[86:89]
	v_mfma_f32_16x16x32_bf16 v[82:85], v[220:223], v[188:191], v[82:85]
	v_mfma_f32_16x16x32_bf16 v[70:73], v[204:207], v[196:199], v[70:73]
	v_mfma_f32_16x16x32_bf16 v[66:69], v[220:223], v[196:199], v[66:69]
	s_mov_b32 m0, s61
	s_add_u32 s98, s40, 0x80
	s_addc_u32 s99, s41, 0
	s_barrier
	ds_read_b128 v[168:171], v145 offset:16384
	ds_read_b128 v[172:175], v145 offset:17408
	ds_read_b128 v[176:179], v145 offset:18432
	ds_read_b128 v[180:183], v145 offset:19456
	ds_read_b128 v[184:187], v145 offset:20480
	ds_read_b128 v[188:191], v145 offset:21504
	ds_read_b128 v[192:195], v145 offset:22528
	global_load_lds_dwordx4 v0, s[40:41]
	s_mov_b32 m0, s64
	ds_read_b128 v[196:199], v145 offset:23552
	global_load_lds_dwordx4 v134, s[40:41]
	s_barrier
	s_waitcnt lgkmcnt(7)
	v_mfma_f32_16x16x32_bf16 v[62:65], v[152:155], v[168:171], v[62:65]
	v_mfma_f32_16x16x32_bf16 v[58:61], v[160:163], v[168:171], v[58:61]
	s_waitcnt lgkmcnt(5)
	v_mfma_f32_16x16x32_bf16 v[46:49], v[152:155], v[176:179], v[46:49]
	v_mfma_f32_16x16x32_bf16 v[42:45], v[160:163], v[176:179], v[42:45]
	s_waitcnt lgkmcnt(3)
	v_mfma_f32_16x16x32_bf16 v[30:33], v[152:155], v[184:187], v[30:33]
	v_mfma_f32_16x16x32_bf16 v[26:29], v[160:163], v[184:187], v[26:29]
	s_waitcnt lgkmcnt(1)
	v_mfma_f32_16x16x32_bf16 v[14:17], v[152:155], v[192:195], v[14:17]
	v_mfma_f32_16x16x32_bf16 v[10:13], v[160:163], v[192:195], v[10:13]
	v_mfma_f32_16x16x32_bf16 v[62:65], v[156:159], v[172:175], v[62:65]
	v_mfma_f32_16x16x32_bf16 v[58:61], v[164:167], v[172:175], v[58:61]
	v_mfma_f32_16x16x32_bf16 v[46:49], v[156:159], v[180:183], v[46:49]
	v_mfma_f32_16x16x32_bf16 v[42:45], v[164:167], v[180:183], v[42:45]
	v_mfma_f32_16x16x32_bf16 v[30:33], v[156:159], v[188:191], v[30:33]
	v_mfma_f32_16x16x32_bf16 v[26:29], v[164:167], v[188:191], v[26:29]
	s_waitcnt lgkmcnt(0)
	v_mfma_f32_16x16x32_bf16 v[14:17], v[156:159], v[196:199], v[14:17]
	v_mfma_f32_16x16x32_bf16 v[10:13], v[164:167], v[196:199], v[10:13]
	s_barrier
	s_add_i32 s81, s81, s60
	s_mov_b32 m0, s81
	s_add_u32 s82, s30, 0x80000
	s_addc_u32 s83, s31, 0
	global_load_lds_dwordx4 v0, s[82:83]
	s_add_i32 m0, s81, 0x2000
	s_nop 0
	global_load_lds_dwordx4 v134, s[82:83]
	s_waitcnt vmcnt(6)
	s_barrier
	v_mfma_f32_16x16x32_bf16 v[54:57], v[200:203], v[168:171], v[54:57]
	v_mfma_f32_16x16x32_bf16 v[50:53], v[216:219], v[168:171], v[50:53]
	v_mfma_f32_16x16x32_bf16 v[38:41], v[200:203], v[176:179], v[38:41]
	v_mfma_f32_16x16x32_bf16 v[34:37], v[216:219], v[176:179], v[34:37]
	v_mfma_f32_16x16x32_bf16 v[22:25], v[200:203], v[184:187], v[22:25]
	v_mfma_f32_16x16x32_bf16 v[18:21], v[216:219], v[184:187], v[18:21]
	v_mfma_f32_16x16x32_bf16 v[6:9], v[200:203], v[192:195], v[6:9]
	v_mfma_f32_16x16x32_bf16 v[2:5], v[216:219], v[192:195], v[2:5]
	v_mfma_f32_16x16x32_bf16 v[54:57], v[204:207], v[172:175], v[54:57]
	v_mfma_f32_16x16x32_bf16 v[50:53], v[220:223], v[172:175], v[50:53]
	v_mfma_f32_16x16x32_bf16 v[38:41], v[204:207], v[180:183], v[38:41]
	v_mfma_f32_16x16x32_bf16 v[34:37], v[220:223], v[180:183], v[34:37]
	v_mfma_f32_16x16x32_bf16 v[22:25], v[204:207], v[188:191], v[22:25]
	v_mfma_f32_16x16x32_bf16 v[18:21], v[220:223], v[188:191], v[18:21]
	v_mfma_f32_16x16x32_bf16 v[6:9], v[204:207], v[196:199], v[6:9]
	v_mfma_f32_16x16x32_bf16 v[2:5], v[220:223], v[196:199], v[2:5]
	s_add_i32 s81, 0, 0x18000
	s_barrier
	ds_read_b128 v[152:155], v226
	ds_read_b128 v[156:159], v226 offset:1024
	ds_read_b128 v[160:163], v226 offset:2048
	ds_read_b128 v[164:167], v226 offset:3072
	s_add_u32 s40, s40, 0x80000
	s_addc_u32 s41, s41, 0
	s_mov_b32 m0, s67
	ds_read_b128 v[168:171], v145 offset:32768
	ds_read_b128 v[172:175], v145 offset:33792
	ds_read_b128 v[176:179], v145 offset:34816
	ds_read_b128 v[180:183], v145 offset:35840
	ds_read_b128 v[184:187], v145 offset:36864
	ds_read_b128 v[188:191], v145 offset:37888
	ds_read_b128 v[192:195], v145 offset:38912
	global_load_lds_dwordx4 v0, s[40:41]
	s_mov_b32 m0, s68
	ds_read_b128 v[196:199], v145 offset:39936
	global_load_lds_dwordx4 v134, s[40:41]
	s_waitcnt lgkmcnt(8)
	s_barrier
	s_waitcnt lgkmcnt(7)
	v_mfma_f32_16x16x32_bf16 v[126:129], v[152:155], v[168:171], v[126:129]
	v_mfma_f32_16x16x32_bf16 v[122:125], v[160:163], v[168:171], v[122:125]
	s_waitcnt lgkmcnt(5)
	v_mfma_f32_16x16x32_bf16 v[110:113], v[152:155], v[176:179], v[110:113]
	v_mfma_f32_16x16x32_bf16 v[106:109], v[160:163], v[176:179], v[106:109]
	s_waitcnt lgkmcnt(3)
	v_mfma_f32_16x16x32_bf16 v[94:97], v[152:155], v[184:187], v[94:97]
	v_mfma_f32_16x16x32_bf16 v[90:93], v[160:163], v[184:187], v[90:93]
	s_waitcnt lgkmcnt(1)
	v_mfma_f32_16x16x32_bf16 v[78:81], v[152:155], v[192:195], v[78:81]
	v_mfma_f32_16x16x32_bf16 v[74:77], v[160:163], v[192:195], v[74:77]
	v_mfma_f32_16x16x32_bf16 v[126:129], v[156:159], v[172:175], v[126:129]
	v_mfma_f32_16x16x32_bf16 v[122:125], v[164:167], v[172:175], v[122:125]
	v_mfma_f32_16x16x32_bf16 v[110:113], v[156:159], v[180:183], v[110:113]
	v_mfma_f32_16x16x32_bf16 v[106:109], v[164:167], v[180:183], v[106:109]
	v_mfma_f32_16x16x32_bf16 v[94:97], v[156:159], v[188:191], v[94:97]
	v_mfma_f32_16x16x32_bf16 v[90:93], v[164:167], v[188:191], v[90:93]
	s_waitcnt lgkmcnt(0)
	v_mfma_f32_16x16x32_bf16 v[78:81], v[156:159], v[196:199], v[78:81]
	v_mfma_f32_16x16x32_bf16 v[74:77], v[164:167], v[196:199], v[74:77]
	s_barrier
	s_add_i32 s40, 0, 0x1c000
	s_add_i32 s41, s81, s60
	s_add_u32 s100, s30, 0x80
	s_addc_u32 s101, s31, 0
	s_mov_b32 m0, s41
	ds_read_b128 v[200:203], v227
	ds_read_b128 v[204:207], v227 offset:1024
	ds_read_b128 v[216:219], v227 offset:2048
	global_load_lds_dwordx4 v0, s[100:101]
	s_add_i32 m0, s41, 0x2000
	ds_read_b128 v[220:223], v227 offset:3072
	global_load_lds_dwordx4 v134, s[100:101]
	s_barrier
	s_waitcnt lgkmcnt(3)
	v_mfma_f32_16x16x32_bf16 v[118:121], v[200:203], v[168:171], v[118:121]
	s_waitcnt lgkmcnt(1)
	v_mfma_f32_16x16x32_bf16 v[114:117], v[216:219], v[168:171], v[114:117]
	v_mfma_f32_16x16x32_bf16 v[102:105], v[200:203], v[176:179], v[102:105]
	v_mfma_f32_16x16x32_bf16 v[98:101], v[216:219], v[176:179], v[98:101]
	v_mfma_f32_16x16x32_bf16 v[86:89], v[200:203], v[184:187], v[86:89]
	v_mfma_f32_16x16x32_bf16 v[82:85], v[216:219], v[184:187], v[82:85]
	v_mfma_f32_16x16x32_bf16 v[70:73], v[200:203], v[192:195], v[70:73]
	v_mfma_f32_16x16x32_bf16 v[66:69], v[216:219], v[192:195], v[66:69]
	v_mfma_f32_16x16x32_bf16 v[118:121], v[204:207], v[172:175], v[118:121]
	s_waitcnt lgkmcnt(0)
	v_mfma_f32_16x16x32_bf16 v[114:117], v[220:223], v[172:175], v[114:117]
	v_mfma_f32_16x16x32_bf16 v[102:105], v[204:207], v[180:183], v[102:105]
	v_mfma_f32_16x16x32_bf16 v[98:101], v[220:223], v[180:183], v[98:101]
	v_mfma_f32_16x16x32_bf16 v[86:89], v[204:207], v[188:191], v[86:89]
	v_mfma_f32_16x16x32_bf16 v[82:85], v[220:223], v[188:191], v[82:85]
	v_mfma_f32_16x16x32_bf16 v[70:73], v[204:207], v[196:199], v[70:73]
	v_mfma_f32_16x16x32_bf16 v[66:69], v[220:223], v[196:199], v[66:69]
	s_mov_b32 m0, s69
	s_barrier
	ds_read_b128 v[168:171], v145 offset:49152
	ds_read_b128 v[172:175], v145 offset:50176
	ds_read_b128 v[176:179], v145 offset:51200
	ds_read_b128 v[180:183], v145 offset:52224
	ds_read_b128 v[184:187], v145 offset:53248
	ds_read_b128 v[188:191], v145 offset:54272
	ds_read_b128 v[192:195], v145 offset:55296
	global_load_lds_dwordx4 v0, s[98:99]
	s_mov_b32 m0, s75
	ds_read_b128 v[196:199], v145 offset:56320
	global_load_lds_dwordx4 v134, s[98:99]
	s_barrier
	s_waitcnt lgkmcnt(7)
	v_mfma_f32_16x16x32_bf16 v[62:65], v[152:155], v[168:171], v[62:65]
	v_mfma_f32_16x16x32_bf16 v[58:61], v[160:163], v[168:171], v[58:61]
	s_waitcnt lgkmcnt(5)
	v_mfma_f32_16x16x32_bf16 v[46:49], v[152:155], v[176:179], v[46:49]
	v_mfma_f32_16x16x32_bf16 v[42:45], v[160:163], v[176:179], v[42:45]
	s_waitcnt lgkmcnt(3)
	v_mfma_f32_16x16x32_bf16 v[30:33], v[152:155], v[184:187], v[30:33]
	v_mfma_f32_16x16x32_bf16 v[26:29], v[160:163], v[184:187], v[26:29]
	s_waitcnt lgkmcnt(1)
	v_mfma_f32_16x16x32_bf16 v[14:17], v[152:155], v[192:195], v[14:17]
	v_mfma_f32_16x16x32_bf16 v[10:13], v[160:163], v[192:195], v[10:13]
	v_mfma_f32_16x16x32_bf16 v[62:65], v[156:159], v[172:175], v[62:65]
	v_mfma_f32_16x16x32_bf16 v[58:61], v[164:167], v[172:175], v[58:61]
	v_mfma_f32_16x16x32_bf16 v[46:49], v[156:159], v[180:183], v[46:49]
	v_mfma_f32_16x16x32_bf16 v[42:45], v[164:167], v[180:183], v[42:45]
	v_mfma_f32_16x16x32_bf16 v[30:33], v[156:159], v[188:191], v[30:33]
	v_mfma_f32_16x16x32_bf16 v[26:29], v[164:167], v[188:191], v[26:29]
	s_waitcnt lgkmcnt(0)
	v_mfma_f32_16x16x32_bf16 v[14:17], v[156:159], v[196:199], v[14:17]
	v_mfma_f32_16x16x32_bf16 v[10:13], v[164:167], v[196:199], v[10:13]
	s_barrier
	s_add_i32 s40, s40, s60
	s_mov_b32 m0, s40
	s_add_u32 s30, s30, 0x80080
	s_addc_u32 s31, s31, 0
	global_load_lds_dwordx4 v0, s[30:31]
	s_add_i32 m0, s40, 0x2000
	s_nop 0
	global_load_lds_dwordx4 v134, s[30:31]
	s_waitcnt vmcnt(6)
	s_barrier
	v_mfma_f32_16x16x32_bf16 v[54:57], v[200:203], v[168:171], v[54:57]
	v_mfma_f32_16x16x32_bf16 v[50:53], v[216:219], v[168:171], v[50:53]
	v_mfma_f32_16x16x32_bf16 v[38:41], v[200:203], v[176:179], v[38:41]
	v_mfma_f32_16x16x32_bf16 v[34:37], v[216:219], v[176:179], v[34:37]
	v_mfma_f32_16x16x32_bf16 v[22:25], v[200:203], v[184:187], v[22:25]
	v_mfma_f32_16x16x32_bf16 v[18:21], v[216:219], v[184:187], v[18:21]
	v_mfma_f32_16x16x32_bf16 v[6:9], v[200:203], v[192:195], v[6:9]
	v_mfma_f32_16x16x32_bf16 v[2:5], v[216:219], v[192:195], v[2:5]
	v_mfma_f32_16x16x32_bf16 v[54:57], v[204:207], v[172:175], v[54:57]
	v_mfma_f32_16x16x32_bf16 v[50:53], v[220:223], v[172:175], v[50:53]
	v_mfma_f32_16x16x32_bf16 v[38:41], v[204:207], v[180:183], v[38:41]
	v_mfma_f32_16x16x32_bf16 v[34:37], v[220:223], v[180:183], v[34:37]
	v_mfma_f32_16x16x32_bf16 v[22:25], v[204:207], v[188:191], v[22:25]
	v_mfma_f32_16x16x32_bf16 v[18:21], v[220:223], v[188:191], v[18:21]
	v_mfma_f32_16x16x32_bf16 v[6:9], v[204:207], v[196:199], v[6:9]
	v_mfma_f32_16x16x32_bf16 v[2:5], v[220:223], v[196:199], v[2:5]
	s_add_i32 s45, s45, 2
	s_add_u32 s26, s26, 0x100
	s_addc_u32 s27, s27, 0
	s_cmp_gt_u32 s45, 29
	s_barrier
	s_cbranch_scc0 .LBB0_807
	s_add_u32 s26, s79, 0xffffff00
	s_addc_u32 s27, s80, -1
	s_and_b64 vcc, exec, s[42:43]
	s_cbranch_vccnz .LBB0_796
	v_mov_b64_e32 v[2:3], 0
	s_mov_b32 s14, s8
	s_mov_b32 s50, s77
	s_mov_b64 s[6:7], s[22:23]
	s_mov_b32 s76, s78
	v_mov_b64_e32 v[4:5], 0
	v_mov_b64_e32 v[6:7], 0
	v_mov_b64_e32 v[8:9], 0
	v_mov_b64_e32 v[10:11], 0
	v_mov_b64_e32 v[12:13], 0
	v_mov_b64_e32 v[14:15], 0
	v_mov_b64_e32 v[16:17], 0
	v_mov_b64_e32 v[18:19], 0
	v_mov_b64_e32 v[20:21], 0
	v_mov_b64_e32 v[22:23], 0
	v_mov_b64_e32 v[24:25], 0
	v_mov_b64_e32 v[26:27], 0
	v_mov_b64_e32 v[28:29], 0
	v_mov_b64_e32 v[30:31], 0
	v_mov_b64_e32 v[32:33], 0
	v_mov_b64_e32 v[34:35], 0
	v_mov_b64_e32 v[36:37], 0
	v_mov_b64_e32 v[38:39], 0
	v_mov_b64_e32 v[40:41], 0
	v_mov_b64_e32 v[42:43], 0
	v_mov_b64_e32 v[44:45], 0
	v_mov_b64_e32 v[46:47], 0
	v_mov_b64_e32 v[48:49], 0
	v_mov_b64_e32 v[50:51], 0
	v_mov_b64_e32 v[52:53], 0
	v_mov_b64_e32 v[54:55], 0
	v_mov_b64_e32 v[56:57], 0
	v_mov_b64_e32 v[58:59], 0
	v_mov_b64_e32 v[60:61], 0
	v_mov_b64_e32 v[62:63], 0
	v_mov_b64_e32 v[64:65], 0
	v_mov_b64_e32 v[66:67], 0
	v_mov_b64_e32 v[68:69], 0
	v_mov_b64_e32 v[70:71], 0
	v_mov_b64_e32 v[72:73], 0
	v_mov_b64_e32 v[74:75], 0
	v_mov_b64_e32 v[76:77], 0
	v_mov_b64_e32 v[78:79], 0
	v_mov_b64_e32 v[80:81], 0
	v_mov_b64_e32 v[82:83], 0
	v_mov_b64_e32 v[84:85], 0
	v_mov_b64_e32 v[86:87], 0
	v_mov_b64_e32 v[88:89], 0
	v_mov_b64_e32 v[90:91], 0
	v_mov_b64_e32 v[92:93], 0
	v_mov_b64_e32 v[94:95], 0
	v_mov_b64_e32 v[96:97], 0
	v_mov_b64_e32 v[98:99], 0
	v_mov_b64_e32 v[100:101], 0
	v_mov_b64_e32 v[102:103], 0
	v_mov_b64_e32 v[104:105], 0
	v_mov_b64_e32 v[106:107], 0
	v_mov_b64_e32 v[108:109], 0
	v_mov_b64_e32 v[110:111], 0
	v_mov_b64_e32 v[112:113], 0
	v_mov_b64_e32 v[114:115], 0
	v_mov_b64_e32 v[116:117], 0
	v_mov_b64_e32 v[118:119], 0
	v_mov_b64_e32 v[120:121], 0
	v_mov_b64_e32 v[122:123], 0
	v_mov_b64_e32 v[124:125], 0
	v_mov_b64_e32 v[126:127], 0
	v_mov_b64_e32 v[128:129], 0
	s_andn2_b64 vcc, exec, s[0:1]
	s_cbranch_vccnz .LBB0_797

.LBB0_938:
	s_ashr_i32 s23, s22, 31
	s_lshl_b64 s[28:29], s[22:23], 20
	s_add_u32 s28, s8, s28
	s_addc_u32 s29, s9, s29
	s_and_b64 s[38:39], s[42:43], exec
	s_cselect_b32 s23, s29, s37
	s_cselect_b32 s42, s28, s36
	s_add_u32 s30, s30, 0x80080
	s_addc_u32 s31, s31, 0
	s_add_u32 s43, s36, 0x100
	v_mov_b64_e32 v[2:3], 0
	s_addc_u32 s67, s37, 0
	s_mov_b32 s68, -2
	v_mov_b64_e32 v[4:5], 0
	v_mov_b64_e32 v[6:7], 0
	v_mov_b64_e32 v[8:9], 0
	v_mov_b64_e32 v[10:11], 0
	v_mov_b64_e32 v[12:13], 0
	v_mov_b64_e32 v[14:15], 0
	v_mov_b64_e32 v[16:17], 0
	v_mov_b64_e32 v[18:19], 0
	v_mov_b64_e32 v[20:21], 0
	v_mov_b64_e32 v[22:23], 0
	v_mov_b64_e32 v[24:25], 0
	v_mov_b64_e32 v[26:27], 0
	v_mov_b64_e32 v[28:29], 0
	v_mov_b64_e32 v[30:31], 0
	v_mov_b64_e32 v[32:33], 0
	v_mov_b64_e32 v[34:35], 0
	v_mov_b64_e32 v[36:37], 0
	v_mov_b64_e32 v[38:39], 0
	v_mov_b64_e32 v[40:41], 0
	v_mov_b64_e32 v[42:43], 0
	v_mov_b64_e32 v[44:45], 0
	v_mov_b64_e32 v[46:47], 0
	v_mov_b64_e32 v[48:49], 0
	v_mov_b64_e32 v[50:51], 0
	v_mov_b64_e32 v[52:53], 0
	v_mov_b64_e32 v[54:55], 0
	v_mov_b64_e32 v[56:57], 0
	v_mov_b64_e32 v[58:59], 0
	v_mov_b64_e32 v[60:61], 0
	v_mov_b64_e32 v[62:63], 0
	v_mov_b64_e32 v[64:65], 0
	v_mov_b64_e32 v[66:67], 0
	v_mov_b64_e32 v[68:69], 0
	v_mov_b64_e32 v[70:71], 0
	v_mov_b64_e32 v[72:73], 0
	v_mov_b64_e32 v[74:75], 0
	v_mov_b64_e32 v[76:77], 0
	v_mov_b64_e32 v[78:79], 0
	v_mov_b64_e32 v[80:81], 0
	v_mov_b64_e32 v[82:83], 0
	v_mov_b64_e32 v[84:85], 0
	v_mov_b64_e32 v[86:87], 0
	v_mov_b64_e32 v[88:89], 0
	v_mov_b64_e32 v[90:91], 0
	v_mov_b64_e32 v[92:93], 0
	v_mov_b64_e32 v[94:95], 0
	v_mov_b64_e32 v[96:97], 0
	v_mov_b64_e32 v[98:99], 0
	v_mov_b64_e32 v[100:101], 0
	v_mov_b64_e32 v[102:103], 0
	v_mov_b64_e32 v[104:105], 0
	v_mov_b64_e32 v[106:107], 0
	v_mov_b64_e32 v[108:109], 0
	v_mov_b64_e32 v[110:111], 0
	v_mov_b64_e32 v[112:113], 0
	v_mov_b64_e32 v[114:115], 0
	v_mov_b64_e32 v[116:117], 0
	v_mov_b64_e32 v[118:119], 0
	v_mov_b64_e32 v[120:121], 0
	v_mov_b64_e32 v[122:123], 0
	v_mov_b64_e32 v[124:125], 0
	v_mov_b64_e32 v[126:127], 0
	v_mov_b64_e32 v[128:129], 0
	v_add_u32_e32 v224, 0x10000, v140
	v_add_u32_e32 v225, 0x14000, v140
	v_add_u32_e32 v226, 0x18000, v140
	v_add_u32_e32 v227, 0x1c000, v140

.LBB0_1070:
	v_lshl_add_u64 v[12:13], s[22:23], 0, v[0:1]
	v_mov_b32_e32 v137, v1
	s_and_b32 s61, s1, 3
	v_and_b32_e32 v11, 48, v6
	v_lshlrev_b32_e32 v20, 6, v6
	s_movk_i32 s1, 0x3c0
	v_lshlrev_b32_e32 v6, 2, v6
	v_lshl_add_u64 v[14:15], s[22:23], 0, v[136:137]
	s_lshl_b32 s64, s0, 6
	s_lshl_b32 s0, s0, 13
	v_and_or_b32 v11, v20, s1, v11
	v_and_b32_e32 v6, 32, v6
	s_add_i32 m0, s53, 0x18000
	v_lshl_add_u64 v[12:13], v[12:13], 0, s[16:17]
	v_lshl_add_u64 v[16:17], s[6:7], 0, v[0:1]
	v_bitop3_b32 v20, v11, s0, v6 bitop3:0xde
	s_lshl_b32 s0, s61, 12
	s_waitcnt vmcnt(4)
	s_barrier
	global_load_lds_dwordx4 v[12:13], off
	v_lshl_add_u64 v[12:13], v[14:15], 0, s[16:17]
	s_add_i32 m0, s53, 0x1a000
	s_add_i32 s67, s53, 0x8000
	s_add_i32 s68, s53, 0xa000
	v_lshl_add_u64 v[18:19], s[6:7], 0, v[136:137]
	v_bitop3_b32 v146, v11, s0, v6 bitop3:0xde
	global_load_lds_dwordx4 v[12:13], off
	v_lshl_add_u64 v[12:13], v[16:17], 0, s[16:17]
	s_mov_b32 m0, s67
	s_add_u32 s0, s22, 0x158080
	global_load_lds_dwordx4 v[12:13], off
	v_lshl_add_u64 v[12:13], v[18:19], 0, s[16:17]
	s_mov_b32 m0, s68
	s_addc_u32 s1, s23, 0
	global_load_lds_dwordx4 v[12:13], off
	s_add_i32 m0, s53, 0x1c000
	v_lshl_add_u64 v[12:13], s[0:1], 0, v[0:1]
	global_load_lds_dwordx4 v[12:13], off
	v_lshl_add_u64 v[12:13], s[0:1], 0, v[136:137]
	s_add_i32 m0, s53, 0x1e000
	s_movk_i32 s8, 0x1580
	global_load_lds_dwordx4 v[12:13], off
	v_lshrrev_b32_e32 v8, 1, v8
	v_mul_lo_u32 v6, v7, s8
	s_mov_b32 s9, 0x15800
	v_mad_u64_u32 v[6:7], s[0:1], v8, s9, v[6:7]
	v_or_b32_e32 v6, v6, v9
	v_add_lshl_u32 v138, v6, v10, 1
	v_lshrrev_b32_e32 v6, 1, v2
	v_mul_lo_u32 v2, v3, s8
	v_mad_u64_u32 v[2:3], s[0:1], v6, s9, v[2:3]
	s_waitcnt vmcnt(6)
	v_or_b32_e32 v2, v2, v4
	v_add_lshl_u32 v140, v2, v5, 1
	v_mov_b64_e32 v[2:3], 0
	v_readlane_b32 s0, v254, 50
	v_mov_b32_e32 v139, v1
	v_mov_b32_e32 v141, v1
	s_mov_b32 s69, 0
	v_add_u32_e32 v147, 0, v20
	v_readlane_b32 s14, v254, 58
	s_mov_b32 s50, s0
	v_mov_b64_e32 v[4:5], 0
	v_mov_b64_e32 v[6:7], 0
	v_mov_b64_e32 v[8:9], 0
	v_mov_b64_e32 v[10:11], 0
	v_mov_b64_e32 v[12:13], 0
	v_mov_b64_e32 v[14:15], 0
	v_mov_b64_e32 v[16:17], 0
	v_mov_b64_e32 v[18:19], 0
	v_mov_b64_e32 v[20:21], 0
	v_mov_b64_e32 v[22:23], 0
	v_mov_b64_e32 v[24:25], 0
	v_mov_b64_e32 v[26:27], 0
	v_mov_b64_e32 v[28:29], 0
	v_mov_b64_e32 v[30:31], 0
	v_mov_b64_e32 v[32:33], 0
	v_mov_b64_e32 v[34:35], 0
	v_mov_b64_e32 v[36:37], 0
	v_mov_b64_e32 v[38:39], 0
	v_mov_b64_e32 v[40:41], 0
	v_mov_b64_e32 v[42:43], 0
	v_mov_b64_e32 v[44:45], 0
	v_mov_b64_e32 v[46:47], 0
	v_mov_b64_e32 v[48:49], 0
	v_mov_b64_e32 v[50:51], 0
	v_mov_b64_e32 v[52:53], 0
	v_mov_b64_e32 v[54:55], 0
	v_mov_b64_e32 v[56:57], 0
	v_mov_b64_e32 v[58:59], 0
	v_mov_b64_e32 v[60:61], 0
	v_mov_b64_e32 v[62:63], 0
	v_mov_b64_e32 v[64:65], 0
	v_mov_b64_e32 v[66:67], 0
	v_mov_b64_e32 v[68:69], 0
	v_mov_b64_e32 v[70:71], 0
	v_mov_b64_e32 v[72:73], 0
	v_mov_b64_e32 v[74:75], 0
	v_mov_b64_e32 v[76:77], 0
	v_mov_b64_e32 v[78:79], 0
	v_mov_b64_e32 v[80:81], 0
	v_mov_b64_e32 v[82:83], 0
	v_mov_b64_e32 v[84:85], 0
	v_mov_b64_e32 v[86:87], 0
	v_mov_b64_e32 v[88:89], 0
	v_mov_b64_e32 v[90:91], 0
	v_mov_b64_e32 v[92:93], 0
	v_mov_b64_e32 v[94:95], 0
	v_mov_b64_e32 v[96:97], 0
	v_mov_b64_e32 v[98:99], 0
	v_mov_b64_e32 v[100:101], 0
	v_mov_b64_e32 v[102:103], 0
	v_mov_b64_e32 v[104:105], 0
	v_mov_b64_e32 v[106:107], 0
	v_mov_b64_e32 v[108:109], 0
	v_mov_b64_e32 v[110:111], 0
	v_mov_b64_e32 v[112:113], 0
	v_mov_b64_e32 v[114:115], 0
	v_mov_b64_e32 v[116:117], 0
	v_mov_b64_e32 v[118:119], 0
	v_mov_b64_e32 v[120:121], 0
	v_mov_b64_e32 v[122:123], 0
	v_mov_b64_e32 v[124:125], 0
	v_mov_b64_e32 v[126:127], 0
	v_mov_b64_e32 v[128:129], 0
	s_barrier
	s_branch .LBB0_1073

.LBB0_1084:
	s_add_u32 s30, s6, s22
	s_addc_u32 s31, s7, s23
	s_add_u32 s30, s30, 0x100
	s_addc_u32 s31, s31, 0
	s_add_u32 s79, s42, s22
	s_addc_u32 s80, s43, s23
	s_add_i32 s81, 0, 0x10000
	ds_read_b128 v[152:155], v224
	ds_read_b128 v[156:159], v224 offset:1024
	ds_read_b128 v[160:163], v224 offset:2048
	ds_read_b128 v[164:167], v224 offset:3072
	s_cmpk_eq_i32 s22, 0x2a00
	s_cselect_b32 s41, s13, s31
	s_cselect_b32 s40, s12, s30
	s_cselect_b32 s31, s9, s80
	s_cselect_b32 s30, s8, s79
	v_lshl_add_u64 v[200:201], v[142:143], 0, s[22:23]
	s_add_i32 m0, s53, 0xc000
	ds_read_b128 v[168:171], v147
	ds_read_b128 v[172:175], v147 offset:1024
	ds_read_b128 v[176:179], v147 offset:2048
	ds_read_b128 v[180:183], v147 offset:3072
	ds_read_b128 v[184:187], v147 offset:4096
	ds_read_b128 v[188:191], v147 offset:5120
	ds_read_b128 v[192:195], v147 offset:6144
	ds_read_b128 v[196:199], v147 offset:7168
	global_load_lds_dwordx4 v[200:201], off
	v_lshl_add_u64 v[200:201], v[144:145], 0, s[22:23]
	s_add_i32 m0, s53, 0xe000
	s_nop 0
	global_load_lds_dwordx4 v[200:201], off
	s_waitcnt lgkmcnt(8)
	s_barrier
	s_waitcnt lgkmcnt(7)
	v_mfma_f32_16x16x32_bf16 v[126:129], v[152:155], v[168:171], v[126:129]
	v_mfma_f32_16x16x32_bf16 v[122:125], v[160:163], v[168:171], v[122:125]
	s_waitcnt lgkmcnt(5)
	v_mfma_f32_16x16x32_bf16 v[110:113], v[152:155], v[176:179], v[110:113]
	v_mfma_f32_16x16x32_bf16 v[106:109], v[160:163], v[176:179], v[106:109]
	s_waitcnt lgkmcnt(3)
	v_mfma_f32_16x16x32_bf16 v[94:97], v[152:155], v[184:187], v[94:97]
	v_mfma_f32_16x16x32_bf16 v[90:93], v[160:163], v[184:187], v[90:93]
	s_waitcnt lgkmcnt(1)
	v_mfma_f32_16x16x32_bf16 v[78:81], v[152:155], v[192:195], v[78:81]
	v_mfma_f32_16x16x32_bf16 v[74:77], v[160:163], v[192:195], v[74:77]
	v_mfma_f32_16x16x32_bf16 v[126:129], v[156:159], v[172:175], v[126:129]
	v_mfma_f32_16x16x32_bf16 v[122:125], v[164:167], v[172:175], v[122:125]
	v_mfma_f32_16x16x32_bf16 v[110:113], v[156:159], v[180:183], v[110:113]
	v_mfma_f32_16x16x32_bf16 v[106:109], v[164:167], v[180:183], v[106:109]
	v_mfma_f32_16x16x32_bf16 v[94:97], v[156:159], v[188:191], v[94:97]
	v_mfma_f32_16x16x32_bf16 v[90:93], v[164:167], v[188:191], v[90:93]
	s_waitcnt lgkmcnt(0)
	v_mfma_f32_16x16x32_bf16 v[78:81], v[156:159], v[196:199], v[78:81]
	v_mfma_f32_16x16x32_bf16 v[74:77], v[164:167], v[196:199], v[74:77]
	s_barrier
	s_add_i32 s79, 0, 0x14000
	s_add_i32 s80, s81, s52
	s_mov_b32 m0, s80
	ds_read_b128 v[200:203], v225
	ds_read_b128 v[204:207], v225 offset:1024
	ds_read_b128 v[216:219], v225 offset:2048
	global_load_lds_dwordx4 v0, s[30:31]
	s_add_i32 m0, s80, 0x2000
	ds_read_b128 v[220:223], v225 offset:3072
	global_load_lds_dwordx4 v136, s[30:31]
	s_barrier
	s_waitcnt lgkmcnt(3)
	v_mfma_f32_16x16x32_bf16 v[118:121], v[200:203], v[168:171], v[118:121]
	s_waitcnt lgkmcnt(1)
	v_mfma_f32_16x16x32_bf16 v[114:117], v[216:219], v[168:171], v[114:117]
	v_mfma_f32_16x16x32_bf16 v[102:105], v[200:203], v[176:179], v[102:105]
	v_mfma_f32_16x16x32_bf16 v[98:101], v[216:219], v[176:179], v[98:101]
	v_mfma_f32_16x16x32_bf16 v[86:89], v[200:203], v[184:187], v[86:89]
	v_mfma_f32_16x16x32_bf16 v[82:85], v[216:219], v[184:187], v[82:85]
	v_mfma_f32_16x16x32_bf16 v[70:73], v[200:203], v[192:195], v[70:73]
	v_mfma_f32_16x16x32_bf16 v[66:69], v[216:219], v[192:195], v[66:69]
	v_mfma_f32_16x16x32_bf16 v[118:121], v[204:207], v[172:175], v[118:121]
	s_waitcnt lgkmcnt(0)
	v_mfma_f32_16x16x32_bf16 v[114:117], v[220:223], v[172:175], v[114:117]
	v_mfma_f32_16x16x32_bf16 v[102:105], v[204:207], v[180:183], v[102:105]
	v_mfma_f32_16x16x32_bf16 v[98:101], v[220:223], v[180:183], v[98:101]
	v_mfma_f32_16x16x32_bf16 v[86:89], v[204:207], v[188:191], v[86:89]
	v_mfma_f32_16x16x32_bf16 v[82:85], v[220:223], v[188:191], v[82:85]
	v_mfma_f32_16x16x32_bf16 v[70:73], v[204:207], v[196:199], v[70:73]
	v_mfma_f32_16x16x32_bf16 v[66:69], v[220:223], v[196:199], v[66:69]
	s_mov_b32 m0, s53
	s_add_u32 s98, s40, 0x80
	s_addc_u32 s99, s41, 0
	s_barrier
	ds_read_b128 v[168:171], v147 offset:16384
	ds_read_b128 v[172:175], v147 offset:17408
	ds_read_b128 v[176:179], v147 offset:18432
	ds_read_b128 v[180:183], v147 offset:19456
	ds_read_b128 v[184:187], v147 offset:20480
	ds_read_b128 v[188:191], v147 offset:21504
	ds_read_b128 v[192:195], v147 offset:22528
	global_load_lds_dwordx4 v0, s[40:41]
	s_mov_b32 m0, s60
	ds_read_b128 v[196:199], v147 offset:23552
	global_load_lds_dwordx4 v136, s[40:41]
	s_barrier
	s_waitcnt lgkmcnt(7)
	v_mfma_f32_16x16x32_bf16 v[62:65], v[152:155], v[168:171], v[62:65]
	v_mfma_f32_16x16x32_bf16 v[58:61], v[160:163], v[168:171], v[58:61]
	s_waitcnt lgkmcnt(5)
	v_mfma_f32_16x16x32_bf16 v[46:49], v[152:155], v[176:179], v[46:49]
	v_mfma_f32_16x16x32_bf16 v[42:45], v[160:163], v[176:179], v[42:45]
	s_waitcnt lgkmcnt(3)
	v_mfma_f32_16x16x32_bf16 v[30:33], v[152:155], v[184:187], v[30:33]
	v_mfma_f32_16x16x32_bf16 v[26:29], v[160:163], v[184:187], v[26:29]
	s_waitcnt lgkmcnt(1)
	v_mfma_f32_16x16x32_bf16 v[14:17], v[152:155], v[192:195], v[14:17]
	v_mfma_f32_16x16x32_bf16 v[10:13], v[160:163], v[192:195], v[10:13]
	v_mfma_f32_16x16x32_bf16 v[62:65], v[156:159], v[172:175], v[62:65]
	v_mfma_f32_16x16x32_bf16 v[58:61], v[164:167], v[172:175], v[58:61]
	v_mfma_f32_16x16x32_bf16 v[46:49], v[156:159], v[180:183], v[46:49]
	v_mfma_f32_16x16x32_bf16 v[42:45], v[164:167], v[180:183], v[42:45]
	v_mfma_f32_16x16x32_bf16 v[30:33], v[156:159], v[188:191], v[30:33]
	v_mfma_f32_16x16x32_bf16 v[26:29], v[164:167], v[188:191], v[26:29]
	s_waitcnt lgkmcnt(0)
	v_mfma_f32_16x16x32_bf16 v[14:17], v[156:159], v[196:199], v[14:17]
	v_mfma_f32_16x16x32_bf16 v[10:13], v[164:167], v[196:199], v[10:13]
	s_barrier
	s_add_i32 s79, s79, s52
	s_mov_b32 m0, s79
	s_add_u32 s80, s30, 0x158000
	s_addc_u32 s81, s31, 0
	global_load_lds_dwordx4 v0, s[80:81]
	s_add_i32 m0, s79, 0x2000
	s_nop 0
	global_load_lds_dwordx4 v136, s[80:81]
	s_waitcnt vmcnt(6)
	s_barrier
	v_mfma_f32_16x16x32_bf16 v[54:57], v[200:203], v[168:171], v[54:57]
	v_mfma_f32_16x16x32_bf16 v[50:53], v[216:219], v[168:171], v[50:53]
	v_mfma_f32_16x16x32_bf16 v[38:41], v[200:203], v[176:179], v[38:41]
	v_mfma_f32_16x16x32_bf16 v[34:37], v[216:219], v[176:179], v[34:37]
	v_mfma_f32_16x16x32_bf16 v[22:25], v[200:203], v[184:187], v[22:25]
	v_mfma_f32_16x16x32_bf16 v[18:21], v[216:219], v[184:187], v[18:21]
	v_mfma_f32_16x16x32_bf16 v[6:9], v[200:203], v[192:195], v[6:9]
	v_mfma_f32_16x16x32_bf16 v[2:5], v[216:219], v[192:195], v[2:5]
	v_mfma_f32_16x16x32_bf16 v[54:57], v[204:207], v[172:175], v[54:57]
	v_mfma_f32_16x16x32_bf16 v[50:53], v[220:223], v[172:175], v[50:53]
	v_mfma_f32_16x16x32_bf16 v[38:41], v[204:207], v[180:183], v[38:41]
	v_mfma_f32_16x16x32_bf16 v[34:37], v[220:223], v[180:183], v[34:37]
	v_mfma_f32_16x16x32_bf16 v[22:25], v[204:207], v[188:191], v[22:25]
	v_mfma_f32_16x16x32_bf16 v[18:21], v[220:223], v[188:191], v[18:21]
	v_mfma_f32_16x16x32_bf16 v[6:9], v[204:207], v[196:199], v[6:9]
	v_mfma_f32_16x16x32_bf16 v[2:5], v[220:223], v[196:199], v[2:5]
	s_add_i32 s79, 0, 0x18000
	s_barrier
	ds_read_b128 v[152:155], v226
	ds_read_b128 v[156:159], v226 offset:1024
	ds_read_b128 v[160:163], v226 offset:2048
	ds_read_b128 v[164:167], v226 offset:3072
	s_add_u32 s40, s40, 0x158000
	s_addc_u32 s41, s41, 0
	s_mov_b32 m0, s65
	ds_read_b128 v[168:171], v147 offset:32768
	ds_read_b128 v[172:175], v147 offset:33792
	ds_read_b128 v[176:179], v147 offset:34816
	ds_read_b128 v[180:183], v147 offset:35840
	ds_read_b128 v[184:187], v147 offset:36864
	ds_read_b128 v[188:191], v147 offset:37888
	ds_read_b128 v[192:195], v147 offset:38912
	global_load_lds_dwordx4 v0, s[40:41]
	s_mov_b32 m0, s66
	ds_read_b128 v[196:199], v147 offset:39936
	global_load_lds_dwordx4 v136, s[40:41]
	s_waitcnt lgkmcnt(8)
	s_barrier
	s_waitcnt lgkmcnt(7)
	v_mfma_f32_16x16x32_bf16 v[126:129], v[152:155], v[168:171], v[126:129]
	v_mfma_f32_16x16x32_bf16 v[122:125], v[160:163], v[168:171], v[122:125]
	s_waitcnt lgkmcnt(5)
	v_mfma_f32_16x16x32_bf16 v[110:113], v[152:155], v[176:179], v[110:113]
	v_mfma_f32_16x16x32_bf16 v[106:109], v[160:163], v[176:179], v[106:109]
	s_waitcnt lgkmcnt(3)
	v_mfma_f32_16x16x32_bf16 v[94:97], v[152:155], v[184:187], v[94:97]
	v_mfma_f32_16x16x32_bf16 v[90:93], v[160:163], v[184:187], v[90:93]
	s_waitcnt lgkmcnt(1)
	v_mfma_f32_16x16x32_bf16 v[78:81], v[152:155], v[192:195], v[78:81]
	v_mfma_f32_16x16x32_bf16 v[74:77], v[160:163], v[192:195], v[74:77]
	v_mfma_f32_16x16x32_bf16 v[126:129], v[156:159], v[172:175], v[126:129]
	v_mfma_f32_16x16x32_bf16 v[122:125], v[164:167], v[172:175], v[122:125]
	v_mfma_f32_16x16x32_bf16 v[110:113], v[156:159], v[180:183], v[110:113]
	v_mfma_f32_16x16x32_bf16 v[106:109], v[164:167], v[180:183], v[106:109]
	v_mfma_f32_16x16x32_bf16 v[94:97], v[156:159], v[188:191], v[94:97]
	v_mfma_f32_16x16x32_bf16 v[90:93], v[164:167], v[188:191], v[90:93]
	s_waitcnt lgkmcnt(0)
	v_mfma_f32_16x16x32_bf16 v[78:81], v[156:159], v[196:199], v[78:81]
	v_mfma_f32_16x16x32_bf16 v[74:77], v[164:167], v[196:199], v[74:77]
	s_barrier
	s_add_i32 s40, 0, 0x1c000
	s_add_i32 s41, s79, s52
	s_add_u32 s100, s30, 0x80
	s_addc_u32 s101, s31, 0
	s_mov_b32 m0, s41
	ds_read_b128 v[200:203], v227
	ds_read_b128 v[204:207], v227 offset:1024
	ds_read_b128 v[216:219], v227 offset:2048
	global_load_lds_dwordx4 v0, s[100:101]
	s_add_i32 m0, s41, 0x2000
	ds_read_b128 v[220:223], v227 offset:3072
	global_load_lds_dwordx4 v136, s[100:101]
	s_barrier
	s_waitcnt lgkmcnt(3)
	v_mfma_f32_16x16x32_bf16 v[118:121], v[200:203], v[168:171], v[118:121]
	s_waitcnt lgkmcnt(1)
	v_mfma_f32_16x16x32_bf16 v[114:117], v[216:219], v[168:171], v[114:117]
	v_mfma_f32_16x16x32_bf16 v[102:105], v[200:203], v[176:179], v[102:105]
	v_mfma_f32_16x16x32_bf16 v[98:101], v[216:219], v[176:179], v[98:101]
	v_mfma_f32_16x16x32_bf16 v[86:89], v[200:203], v[184:187], v[86:89]
	v_mfma_f32_16x16x32_bf16 v[82:85], v[216:219], v[184:187], v[82:85]
	v_mfma_f32_16x16x32_bf16 v[70:73], v[200:203], v[192:195], v[70:73]
	v_mfma_f32_16x16x32_bf16 v[66:69], v[216:219], v[192:195], v[66:69]
	v_mfma_f32_16x16x32_bf16 v[118:121], v[204:207], v[172:175], v[118:121]
	s_waitcnt lgkmcnt(0)
	v_mfma_f32_16x16x32_bf16 v[114:117], v[220:223], v[172:175], v[114:117]
	v_mfma_f32_16x16x32_bf16 v[102:105], v[204:207], v[180:183], v[102:105]
	v_mfma_f32_16x16x32_bf16 v[98:101], v[220:223], v[180:183], v[98:101]
	v_mfma_f32_16x16x32_bf16 v[86:89], v[204:207], v[188:191], v[86:89]
	v_mfma_f32_16x16x32_bf16 v[82:85], v[220:223], v[188:191], v[82:85]
	v_mfma_f32_16x16x32_bf16 v[70:73], v[204:207], v[196:199], v[70:73]
	v_mfma_f32_16x16x32_bf16 v[66:69], v[220:223], v[196:199], v[66:69]
	s_mov_b32 m0, s67
	s_barrier
	ds_read_b128 v[168:171], v147 offset:49152
	ds_read_b128 v[172:175], v147 offset:50176
	ds_read_b128 v[176:179], v147 offset:51200
	ds_read_b128 v[180:183], v147 offset:52224
	ds_read_b128 v[184:187], v147 offset:53248
	ds_read_b128 v[188:191], v147 offset:54272
	ds_read_b128 v[192:195], v147 offset:55296
	global_load_lds_dwordx4 v0, s[98:99]
	s_mov_b32 m0, s68
	ds_read_b128 v[196:199], v147 offset:56320
	global_load_lds_dwordx4 v136, s[98:99]
	s_barrier
	s_waitcnt lgkmcnt(7)
	v_mfma_f32_16x16x32_bf16 v[62:65], v[152:155], v[168:171], v[62:65]
	v_mfma_f32_16x16x32_bf16 v[58:61], v[160:163], v[168:171], v[58:61]
	s_waitcnt lgkmcnt(5)
	v_mfma_f32_16x16x32_bf16 v[46:49], v[152:155], v[176:179], v[46:49]
	v_mfma_f32_16x16x32_bf16 v[42:45], v[160:163], v[176:179], v[42:45]
	s_waitcnt lgkmcnt(3)
	v_mfma_f32_16x16x32_bf16 v[30:33], v[152:155], v[184:187], v[30:33]
	v_mfma_f32_16x16x32_bf16 v[26:29], v[160:163], v[184:187], v[26:29]
	s_waitcnt lgkmcnt(1)
	v_mfma_f32_16x16x32_bf16 v[14:17], v[152:155], v[192:195], v[14:17]
	v_mfma_f32_16x16x32_bf16 v[10:13], v[160:163], v[192:195], v[10:13]
	v_mfma_f32_16x16x32_bf16 v[62:65], v[156:159], v[172:175], v[62:65]
	v_mfma_f32_16x16x32_bf16 v[58:61], v[164:167], v[172:175], v[58:61]
	v_mfma_f32_16x16x32_bf16 v[46:49], v[156:159], v[180:183], v[46:49]
	v_mfma_f32_16x16x32_bf16 v[42:45], v[164:167], v[180:183], v[42:45]
	v_mfma_f32_16x16x32_bf16 v[30:33], v[156:159], v[188:191], v[30:33]
	v_mfma_f32_16x16x32_bf16 v[26:29], v[164:167], v[188:191], v[26:29]
	s_waitcnt lgkmcnt(0)
	v_mfma_f32_16x16x32_bf16 v[14:17], v[156:159], v[196:199], v[14:17]
	v_mfma_f32_16x16x32_bf16 v[10:13], v[164:167], v[196:199], v[10:13]
	s_barrier
	s_add_i32 s40, s40, s52
	s_mov_b32 m0, s40
	s_add_u32 s30, s30, 0x158080
	s_addc_u32 s31, s31, 0
	global_load_lds_dwordx4 v0, s[30:31]
	s_add_i32 m0, s40, 0x2000
	s_nop 0
	global_load_lds_dwordx4 v136, s[30:31]
	s_waitcnt vmcnt(6)
	s_barrier
	v_mfma_f32_16x16x32_bf16 v[54:57], v[200:203], v[168:171], v[54:57]
	v_mfma_f32_16x16x32_bf16 v[50:53], v[216:219], v[168:171], v[50:53]
	v_mfma_f32_16x16x32_bf16 v[38:41], v[200:203], v[176:179], v[38:41]
	v_mfma_f32_16x16x32_bf16 v[34:37], v[216:219], v[176:179], v[34:37]
	v_mfma_f32_16x16x32_bf16 v[22:25], v[200:203], v[184:187], v[22:25]
	v_mfma_f32_16x16x32_bf16 v[18:21], v[216:219], v[184:187], v[18:21]
	v_mfma_f32_16x16x32_bf16 v[6:9], v[200:203], v[192:195], v[6:9]
	v_mfma_f32_16x16x32_bf16 v[2:5], v[216:219], v[192:195], v[2:5]
	v_mfma_f32_16x16x32_bf16 v[54:57], v[204:207], v[172:175], v[54:57]
	v_mfma_f32_16x16x32_bf16 v[50:53], v[220:223], v[172:175], v[50:53]
	v_mfma_f32_16x16x32_bf16 v[38:41], v[204:207], v[180:183], v[38:41]
	v_mfma_f32_16x16x32_bf16 v[34:37], v[220:223], v[180:183], v[34:37]
	v_mfma_f32_16x16x32_bf16 v[22:25], v[204:207], v[188:191], v[22:25]
	v_mfma_f32_16x16x32_bf16 v[18:21], v[220:223], v[188:191], v[18:21]
	v_mfma_f32_16x16x32_bf16 v[6:9], v[204:207], v[196:199], v[6:9]
	v_mfma_f32_16x16x32_bf16 v[2:5], v[220:223], v[196:199], v[2:5]
	s_add_i32 s78, s78, 2
	s_add_u32 s22, s22, 0x100
	s_addc_u32 s23, s23, 0
	s_cmpk_gt_u32 s78, 0x53
	s_barrier
	s_cbranch_scc0 .LBB0_1084
	s_add_u32 s22, s42, 0xffffff00
	s_addc_u32 s23, s43, -1
	s_and_b64 vcc, exec, s[38:39]
	s_cbranch_vccnz .LBB0_1071
	v_mov_b64_e32 v[2:3], 0
	s_mov_b32 s14, s75
	s_mov_b32 s50, s76
	s_mov_b64 s[6:7], s[12:13]
	s_mov_b32 s69, s77
	v_mov_b64_e32 v[4:5], 0
	v_mov_b64_e32 v[6:7], 0
	v_mov_b64_e32 v[8:9], 0
	v_mov_b64_e32 v[10:11], 0
	v_mov_b64_e32 v[12:13], 0
	v_mov_b64_e32 v[14:15], 0
	v_mov_b64_e32 v[16:17], 0
	v_mov_b64_e32 v[18:19], 0
	v_mov_b64_e32 v[20:21], 0
	v_mov_b64_e32 v[22:23], 0
	v_mov_b64_e32 v[24:25], 0
	v_mov_b64_e32 v[26:27], 0
	v_mov_b64_e32 v[28:29], 0
	v_mov_b64_e32 v[30:31], 0
	v_mov_b64_e32 v[32:33], 0
	v_mov_b64_e32 v[34:35], 0
	v_mov_b64_e32 v[36:37], 0
	v_mov_b64_e32 v[38:39], 0
	v_mov_b64_e32 v[40:41], 0
	v_mov_b64_e32 v[42:43], 0
	v_mov_b64_e32 v[44:45], 0
	v_mov_b64_e32 v[46:47], 0
	v_mov_b64_e32 v[48:49], 0
	v_mov_b64_e32 v[50:51], 0
	v_mov_b64_e32 v[52:53], 0
	v_mov_b64_e32 v[54:55], 0
	v_mov_b64_e32 v[56:57], 0
	v_mov_b64_e32 v[58:59], 0
	v_mov_b64_e32 v[60:61], 0
	v_mov_b64_e32 v[62:63], 0
	v_mov_b64_e32 v[64:65], 0
	v_mov_b64_e32 v[66:67], 0
	v_mov_b64_e32 v[68:69], 0
	v_mov_b64_e32 v[70:71], 0
	v_mov_b64_e32 v[72:73], 0
	v_mov_b64_e32 v[74:75], 0
	v_mov_b64_e32 v[76:77], 0
	v_mov_b64_e32 v[78:79], 0
	v_mov_b64_e32 v[80:81], 0
	v_mov_b64_e32 v[82:83], 0
	v_mov_b64_e32 v[84:85], 0
	v_mov_b64_e32 v[86:87], 0
	v_mov_b64_e32 v[88:89], 0
	v_mov_b64_e32 v[90:91], 0
	v_mov_b64_e32 v[92:93], 0
	v_mov_b64_e32 v[94:95], 0
	v_mov_b64_e32 v[96:97], 0
	v_mov_b64_e32 v[98:99], 0
	v_mov_b64_e32 v[100:101], 0
	v_mov_b64_e32 v[102:103], 0
	v_mov_b64_e32 v[104:105], 0
	v_mov_b64_e32 v[106:107], 0
	v_mov_b64_e32 v[108:109], 0
	v_mov_b64_e32 v[110:111], 0
	v_mov_b64_e32 v[112:113], 0
	v_mov_b64_e32 v[114:115], 0
	v_mov_b64_e32 v[116:117], 0
	v_mov_b64_e32 v[118:119], 0
	v_mov_b64_e32 v[120:121], 0
	v_mov_b64_e32 v[122:123], 0
	v_mov_b64_e32 v[124:125], 0
	v_mov_b64_e32 v[126:127], 0
	v_mov_b64_e32 v[128:129], 0
	s_andn2_b64 vcc, exec, s[0:1]
	s_cbranch_vccnz .LBB0_1072
